# first K-iteration of the 8 static GEMM loops peeled: first-touch MFMAs take C=0, the 128 per-tile accumulator-zeroing v_mov removed
# speedup vs baseline: 1.0063x; 1.0063x over previous
.LBB0_230:
	s_ashr_i32 s25, s24, 31
	s_lshl_b64 s[26:27], s[24:25], 19
	s_add_u32 s26, s42, s26
	s_addc_u32 s27, s43, s27
	s_and_b64 s[28:29], s[4:5], exec
	s_cselect_b32 s7, s27, s31
	s_cselect_b32 s25, s26, s30
	s_ashr_i32 s9, s8, 31
	s_lshl_b64 s[28:29], s[8:9], 19
	s_add_u32 s28, s51, s28
	s_addc_u32 s29, s52, s29
	s_and_b64 s[48:49], s[4:5], exec
	s_cselect_b32 s9, s29, s47
	s_cselect_b32 s63, s28, s46
	s_add_u32 s30, s30, 0x40080
	s_addc_u32 s31, s31, 0
	s_add_u32 s64, s46, 0x100
	s_addc_u32 s65, s47, 0
	s_mov_b32 s66, -2
	s_waitcnt lgkmcnt(0)
	ds_read_b128 v[142:145], v172
	ds_read_b128 v[146:149], v172 offset:1024
	ds_read_b128 v[150:153], v172 offset:2048
	ds_read_b128 v[154:157], v172 offset:3072
	ds_read_b128 v[158:161], v173
	ds_read_b128 v[176:179], v173 offset:1024
	ds_read_b128 v[180:183], v173 offset:2048
	ds_read_b128 v[184:187], v173 offset:3072
	s_add_u32 s46, s30, 0xfffc0080
	s_addc_u32 s47, s31, -1
	s_cmp_eq_u32 s66, 12
	s_cselect_b32 s49, s7, s47
	s_cselect_b32 s48, s25, s46
	s_cselect_b32 s47, s9, s65
	s_cselect_b32 s46, s63, s64
	v_lshl_add_u64 v[162:163], s[30:31], 0, v[136:137]
	s_add_i32 m0, s15, 0xc000
	ds_read_b128 v[188:191], v174
	ds_read_b128 v[192:195], v174 offset:1024
	ds_read_b128 v[196:199], v174 offset:2048
	ds_read_b128 v[200:203], v174 offset:3072
	ds_read_b128 v[204:207], v174 offset:4096
	ds_read_b128 v[208:211], v174 offset:5120
	ds_read_b128 v[216:219], v174 offset:6144
	ds_read_b128 v[220:223], v174 offset:7168
	global_load_lds_dwordx4 v[162:163], off
	v_lshl_add_u64 v[162:163], s[30:31], 0, v[138:139]
	s_add_i32 m0, s15, 0xe000
	s_nop 0
	global_load_lds_dwordx4 v[162:163], off
	s_waitcnt vmcnt(8)
	s_waitcnt lgkmcnt(0)
	s_barrier
	s_setprio 1
	s_waitcnt lgkmcnt(0)
	v_mfma_f32_16x16x32_bf16 v[124:127], v[142:145], v[188:191], 0
	v_mfma_f32_16x16x32_bf16 v[120:123], v[150:153], v[188:191], 0
	v_mfma_f32_16x16x32_bf16 v[108:111], v[142:145], v[196:199], 0
	v_mfma_f32_16x16x32_bf16 v[104:107], v[150:153], v[196:199], 0
	v_mfma_f32_16x16x32_bf16 v[92:95], v[142:145], v[204:207], 0
	v_mfma_f32_16x16x32_bf16 v[88:91], v[150:153], v[204:207], 0
	v_mfma_f32_16x16x32_bf16 v[76:79], v[142:145], v[216:219], 0
	v_mfma_f32_16x16x32_bf16 v[72:75], v[150:153], v[216:219], 0
	v_mfma_f32_16x16x32_bf16 v[124:127], v[146:149], v[192:195], v[124:127]
	v_mfma_f32_16x16x32_bf16 v[120:123], v[154:157], v[192:195], v[120:123]
	v_mfma_f32_16x16x32_bf16 v[108:111], v[146:149], v[200:203], v[108:111]
	v_mfma_f32_16x16x32_bf16 v[104:107], v[154:157], v[200:203], v[104:107]
	v_mfma_f32_16x16x32_bf16 v[92:95], v[146:149], v[208:211], v[92:95]
	v_mfma_f32_16x16x32_bf16 v[88:91], v[154:157], v[208:211], v[88:91]
	v_mfma_f32_16x16x32_bf16 v[76:79], v[146:149], v[220:223], v[76:79]
	v_mfma_f32_16x16x32_bf16 v[72:75], v[154:157], v[220:223], v[72:75]
	s_setprio 0
	s_setprio 1
	v_mfma_f32_16x16x32_bf16 v[116:119], v[158:161], v[188:191], 0
	v_mfma_f32_16x16x32_bf16 v[112:115], v[180:183], v[188:191], 0
	v_mfma_f32_16x16x32_bf16 v[100:103], v[158:161], v[196:199], 0
	v_mfma_f32_16x16x32_bf16 v[96:99], v[180:183], v[196:199], 0
	v_mfma_f32_16x16x32_bf16 v[84:87], v[158:161], v[204:207], 0
	v_mfma_f32_16x16x32_bf16 v[80:83], v[180:183], v[204:207], 0
	v_mfma_f32_16x16x32_bf16 v[68:71], v[158:161], v[216:219], 0
	v_mfma_f32_16x16x32_bf16 v[64:67], v[180:183], v[216:219], 0
	v_mfma_f32_16x16x32_bf16 v[116:119], v[176:179], v[192:195], v[116:119]
	v_mfma_f32_16x16x32_bf16 v[112:115], v[184:187], v[192:195], v[112:115]
	v_mfma_f32_16x16x32_bf16 v[100:103], v[176:179], v[200:203], v[100:103]
	v_mfma_f32_16x16x32_bf16 v[96:99], v[184:187], v[200:203], v[96:99]
	v_mfma_f32_16x16x32_bf16 v[84:87], v[176:179], v[208:211], v[84:87]
	v_mfma_f32_16x16x32_bf16 v[80:83], v[184:187], v[208:211], v[80:83]
	v_mfma_f32_16x16x32_bf16 v[68:71], v[176:179], v[220:223], v[68:71]
	v_mfma_f32_16x16x32_bf16 v[64:67], v[184:187], v[220:223], v[64:67]
	s_setprio 0
	s_barrier
	s_add_i32 s67, s12, s53
	v_lshl_add_u64 v[162:163], s[46:47], 0, v[128:129]
	s_mov_b32 m0, s67
	ds_read_b128 v[188:191], v174 offset:16384
	ds_read_b128 v[192:195], v174 offset:17408
	ds_read_b128 v[196:199], v174 offset:18432
	ds_read_b128 v[200:203], v174 offset:19456
	ds_read_b128 v[204:207], v174 offset:20480
	ds_read_b128 v[208:211], v174 offset:21504
	ds_read_b128 v[216:219], v174 offset:22528
	ds_read_b128 v[220:223], v174 offset:23552
	global_load_lds_dwordx4 v[162:163], off
	s_add_i32 m0, s67, 0x2000
	s_add_u32 s68, s46, 0x40000
	v_lshl_add_u64 v[212:213], s[46:47], 0, v[130:131]
	s_addc_u32 s69, s47, 0
	s_add_i32 s67, s62, s53
	global_load_lds_dwordx4 v[212:213], off
	v_lshl_add_u64 v[224:225], s[68:69], 0, v[128:129]
	s_mov_b32 m0, s67
	v_lshl_add_u64 v[226:227], s[48:49], 0, v[130:131]
	global_load_lds_dwordx4 v[224:225], off
	v_lshl_add_u64 v[224:225], s[68:69], 0, v[130:131]
	s_add_i32 m0, s67, 0x2000
	s_nop 0
	global_load_lds_dwordx4 v[224:225], off
	v_lshl_add_u64 v[224:225], s[48:49], 0, v[128:129]
	s_mov_b32 m0, s15
	s_nop 0
	global_load_lds_dwordx4 v[224:225], off
	s_mov_b32 m0, s54
	s_nop 0
	global_load_lds_dwordx4 v[226:227], off
	s_waitcnt vmcnt(8)
	s_waitcnt lgkmcnt(0)
	s_barrier
	s_setprio 1
	s_waitcnt lgkmcnt(0)
	v_mfma_f32_16x16x32_bf16 v[60:63], v[142:145], v[188:191], 0
	v_mfma_f32_16x16x32_bf16 v[56:59], v[150:153], v[188:191], 0
	v_mfma_f32_16x16x32_bf16 v[44:47], v[142:145], v[196:199], 0
	v_mfma_f32_16x16x32_bf16 v[40:43], v[150:153], v[196:199], 0
	v_mfma_f32_16x16x32_bf16 v[28:31], v[142:145], v[204:207], 0
	v_mfma_f32_16x16x32_bf16 v[24:27], v[150:153], v[204:207], 0
	v_mfma_f32_16x16x32_bf16 v[12:15], v[142:145], v[216:219], 0
	v_mfma_f32_16x16x32_bf16 v[8:11], v[150:153], v[216:219], 0
	v_mfma_f32_16x16x32_bf16 v[60:63], v[146:149], v[192:195], v[60:63]
	v_mfma_f32_16x16x32_bf16 v[56:59], v[154:157], v[192:195], v[56:59]
	v_mfma_f32_16x16x32_bf16 v[44:47], v[146:149], v[200:203], v[44:47]
	v_mfma_f32_16x16x32_bf16 v[40:43], v[154:157], v[200:203], v[40:43]
	v_mfma_f32_16x16x32_bf16 v[28:31], v[146:149], v[208:211], v[28:31]
	v_mfma_f32_16x16x32_bf16 v[24:27], v[154:157], v[208:211], v[24:27]
	v_mfma_f32_16x16x32_bf16 v[12:15], v[146:149], v[220:223], v[12:15]
	v_mfma_f32_16x16x32_bf16 v[8:11], v[154:157], v[220:223], v[8:11]
	s_setprio 0
	s_setprio 1
	v_mfma_f32_16x16x32_bf16 v[52:55], v[158:161], v[188:191], 0
	v_mfma_f32_16x16x32_bf16 v[48:51], v[180:183], v[188:191], 0
	v_mfma_f32_16x16x32_bf16 v[36:39], v[158:161], v[196:199], 0
	v_mfma_f32_16x16x32_bf16 v[32:35], v[180:183], v[196:199], 0
	v_mfma_f32_16x16x32_bf16 v[20:23], v[158:161], v[204:207], 0
	v_mfma_f32_16x16x32_bf16 v[16:19], v[180:183], v[204:207], 0
	v_mfma_f32_16x16x32_bf16 v[4:7], v[158:161], v[216:219], 0
	v_mfma_f32_16x16x32_bf16 v[0:3], v[180:183], v[216:219], 0
	v_mfma_f32_16x16x32_bf16 v[52:55], v[176:179], v[192:195], v[52:55]
	v_mfma_f32_16x16x32_bf16 v[48:51], v[184:187], v[192:195], v[48:51]
	v_mfma_f32_16x16x32_bf16 v[36:39], v[176:179], v[200:203], v[36:39]
	v_mfma_f32_16x16x32_bf16 v[32:35], v[184:187], v[200:203], v[32:35]
	v_mfma_f32_16x16x32_bf16 v[20:23], v[176:179], v[208:211], v[20:23]
	v_mfma_f32_16x16x32_bf16 v[16:19], v[184:187], v[208:211], v[16:19]
	v_mfma_f32_16x16x32_bf16 v[4:7], v[176:179], v[220:223], v[4:7]
	v_mfma_f32_16x16x32_bf16 v[0:3], v[184:187], v[220:223], v[0:3]
	s_setprio 0
	s_barrier
	s_add_i32 s67, 0, 0x18000
	v_add_u32_e32 v132, s67, v167
	s_add_i32 s68, 0, 0x1c000
	ds_read_b128 v[142:145], v132
	ds_read_b128 v[146:149], v132 offset:1024
	ds_read_b128 v[150:153], v132 offset:2048
	ds_read_b128 v[154:157], v132 offset:3072
	v_add_u32_e32 v132, s68, v167
	ds_read_b128 v[158:161], v132
	ds_read_b128 v[176:179], v132 offset:1024
	ds_read_b128 v[180:183], v132 offset:2048
	ds_read_b128 v[184:187], v132 offset:3072
	s_add_u32 s48, s48, 0x40000
	s_addc_u32 s49, s49, 0
	s_mov_b32 m0, s55
	v_lshl_add_u64 v[228:229], s[48:49], 0, v[128:129]
	ds_read_b128 v[188:191], v174 offset:32768
	ds_read_b128 v[192:195], v174 offset:33792
	ds_read_b128 v[196:199], v174 offset:34816
	ds_read_b128 v[200:203], v174 offset:35840
	ds_read_b128 v[204:207], v174 offset:36864
	ds_read_b128 v[208:211], v174 offset:37888
	ds_read_b128 v[216:219], v174 offset:38912
	ds_read_b128 v[220:223], v174 offset:39936
	global_load_lds_dwordx4 v[228:229], off
	v_lshl_add_u64 v[228:229], s[48:49], 0, v[130:131]
	s_mov_b32 m0, s56
	s_nop 0
	global_load_lds_dwordx4 v[228:229], off
	s_waitcnt vmcnt(8)
	s_waitcnt lgkmcnt(0)
	s_barrier
	s_setprio 1
	s_waitcnt lgkmcnt(0)
	v_mfma_f32_16x16x32_bf16 v[124:127], v[142:145], v[188:191], v[124:127]
	v_mfma_f32_16x16x32_bf16 v[120:123], v[150:153], v[188:191], v[120:123]
	v_mfma_f32_16x16x32_bf16 v[108:111], v[142:145], v[196:199], v[108:111]
	v_mfma_f32_16x16x32_bf16 v[104:107], v[150:153], v[196:199], v[104:107]
	v_mfma_f32_16x16x32_bf16 v[92:95], v[142:145], v[204:207], v[92:95]
	v_mfma_f32_16x16x32_bf16 v[88:91], v[150:153], v[204:207], v[88:91]
	v_mfma_f32_16x16x32_bf16 v[76:79], v[142:145], v[216:219], v[76:79]
	v_mfma_f32_16x16x32_bf16 v[72:75], v[150:153], v[216:219], v[72:75]
	v_mfma_f32_16x16x32_bf16 v[124:127], v[146:149], v[192:195], v[124:127]
	v_mfma_f32_16x16x32_bf16 v[120:123], v[154:157], v[192:195], v[120:123]
	v_mfma_f32_16x16x32_bf16 v[108:111], v[146:149], v[200:203], v[108:111]
	v_mfma_f32_16x16x32_bf16 v[104:107], v[154:157], v[200:203], v[104:107]
	v_mfma_f32_16x16x32_bf16 v[92:95], v[146:149], v[208:211], v[92:95]
	v_mfma_f32_16x16x32_bf16 v[88:91], v[154:157], v[208:211], v[88:91]
	v_mfma_f32_16x16x32_bf16 v[76:79], v[146:149], v[220:223], v[76:79]
	v_mfma_f32_16x16x32_bf16 v[72:75], v[154:157], v[220:223], v[72:75]
	s_setprio 0
	s_setprio 1
	v_mfma_f32_16x16x32_bf16 v[116:119], v[158:161], v[188:191], v[116:119]
	v_mfma_f32_16x16x32_bf16 v[112:115], v[180:183], v[188:191], v[112:115]
	v_mfma_f32_16x16x32_bf16 v[100:103], v[158:161], v[196:199], v[100:103]
	v_mfma_f32_16x16x32_bf16 v[96:99], v[180:183], v[196:199], v[96:99]
	v_mfma_f32_16x16x32_bf16 v[84:87], v[158:161], v[204:207], v[84:87]
	v_mfma_f32_16x16x32_bf16 v[80:83], v[180:183], v[204:207], v[80:83]
	v_mfma_f32_16x16x32_bf16 v[68:71], v[158:161], v[216:219], v[68:71]
	v_mfma_f32_16x16x32_bf16 v[64:67], v[180:183], v[216:219], v[64:67]
	v_mfma_f32_16x16x32_bf16 v[116:119], v[176:179], v[192:195], v[116:119]
	v_mfma_f32_16x16x32_bf16 v[112:115], v[184:187], v[192:195], v[112:115]
	v_mfma_f32_16x16x32_bf16 v[100:103], v[176:179], v[200:203], v[100:103]
	v_mfma_f32_16x16x32_bf16 v[96:99], v[184:187], v[200:203], v[96:99]
	v_mfma_f32_16x16x32_bf16 v[84:87], v[176:179], v[208:211], v[84:87]
	v_mfma_f32_16x16x32_bf16 v[80:83], v[184:187], v[208:211], v[80:83]
	v_mfma_f32_16x16x32_bf16 v[68:71], v[176:179], v[220:223], v[68:71]
	v_mfma_f32_16x16x32_bf16 v[64:67], v[184:187], v[220:223], v[64:67]
	s_setprio 0
	s_barrier
	s_add_i32 s48, s67, s53
	v_lshl_add_u64 v[162:163], v[162:163], 0, s[20:21]
	s_mov_b32 m0, s48
	ds_read_b128 v[188:191], v174 offset:49152
	ds_read_b128 v[192:195], v174 offset:50176
	ds_read_b128 v[196:199], v174 offset:51200
	ds_read_b128 v[200:203], v174 offset:52224
	ds_read_b128 v[204:207], v174 offset:53248
	ds_read_b128 v[208:211], v174 offset:54272
	ds_read_b128 v[216:219], v174 offset:55296
	ds_read_b128 v[220:223], v174 offset:56320
	global_load_lds_dwordx4 v[162:163], off
	s_add_i32 m0, s48, 0x2000
	s_add_u32 s46, s46, 0x40080
	v_lshl_add_u64 v[162:163], v[212:213], 0, s[20:21]
	s_addc_u32 s47, s47, 0
	s_add_i32 s48, s68, s53
	global_load_lds_dwordx4 v[162:163], off
	v_lshl_add_u64 v[162:163], s[46:47], 0, v[128:129]
	s_mov_b32 m0, s48
	s_nop 0
	global_load_lds_dwordx4 v[162:163], off
	v_lshl_add_u64 v[162:163], s[46:47], 0, v[130:131]
	s_add_i32 m0, s48, 0x2000
	s_nop 0
	global_load_lds_dwordx4 v[162:163], off
	v_lshl_add_u64 v[162:163], v[224:225], 0, s[20:21]
	s_mov_b32 m0, s60
	s_nop 0
	global_load_lds_dwordx4 v[162:163], off
	v_lshl_add_u64 v[162:163], v[226:227], 0, s[20:21]
	s_mov_b32 m0, s61
	s_nop 0
	global_load_lds_dwordx4 v[162:163], off
	s_waitcnt vmcnt(8)
	s_waitcnt lgkmcnt(0)
	s_barrier
	s_setprio 1
	s_waitcnt lgkmcnt(0)
	v_mfma_f32_16x16x32_bf16 v[60:63], v[142:145], v[188:191], v[60:63]
	v_mfma_f32_16x16x32_bf16 v[56:59], v[150:153], v[188:191], v[56:59]
	v_mfma_f32_16x16x32_bf16 v[44:47], v[142:145], v[196:199], v[44:47]
	v_mfma_f32_16x16x32_bf16 v[40:43], v[150:153], v[196:199], v[40:43]
	v_mfma_f32_16x16x32_bf16 v[28:31], v[142:145], v[204:207], v[28:31]
	v_mfma_f32_16x16x32_bf16 v[24:27], v[150:153], v[204:207], v[24:27]
	v_mfma_f32_16x16x32_bf16 v[12:15], v[142:145], v[216:219], v[12:15]
	v_mfma_f32_16x16x32_bf16 v[8:11], v[150:153], v[216:219], v[8:11]
	v_mfma_f32_16x16x32_bf16 v[60:63], v[146:149], v[192:195], v[60:63]
	v_mfma_f32_16x16x32_bf16 v[56:59], v[154:157], v[192:195], v[56:59]
	v_mfma_f32_16x16x32_bf16 v[44:47], v[146:149], v[200:203], v[44:47]
	v_mfma_f32_16x16x32_bf16 v[40:43], v[154:157], v[200:203], v[40:43]
	v_mfma_f32_16x16x32_bf16 v[28:31], v[146:149], v[208:211], v[28:31]
	v_mfma_f32_16x16x32_bf16 v[24:27], v[154:157], v[208:211], v[24:27]
	v_mfma_f32_16x16x32_bf16 v[12:15], v[146:149], v[220:223], v[12:15]
	v_mfma_f32_16x16x32_bf16 v[8:11], v[154:157], v[220:223], v[8:11]
	s_setprio 0
	s_setprio 1
	v_mfma_f32_16x16x32_bf16 v[52:55], v[158:161], v[188:191], v[52:55]
	v_mfma_f32_16x16x32_bf16 v[48:51], v[180:183], v[188:191], v[48:51]
	v_mfma_f32_16x16x32_bf16 v[36:39], v[158:161], v[196:199], v[36:39]
	v_mfma_f32_16x16x32_bf16 v[32:35], v[180:183], v[196:199], v[32:35]
	v_mfma_f32_16x16x32_bf16 v[20:23], v[158:161], v[204:207], v[20:23]
	v_mfma_f32_16x16x32_bf16 v[16:19], v[180:183], v[204:207], v[16:19]
	v_mfma_f32_16x16x32_bf16 v[4:7], v[158:161], v[216:219], v[4:7]
	v_mfma_f32_16x16x32_bf16 v[0:3], v[180:183], v[216:219], v[0:3]
	v_mfma_f32_16x16x32_bf16 v[52:55], v[176:179], v[192:195], v[52:55]
	v_mfma_f32_16x16x32_bf16 v[48:51], v[184:187], v[192:195], v[48:51]
	v_mfma_f32_16x16x32_bf16 v[36:39], v[176:179], v[200:203], v[36:39]
	v_mfma_f32_16x16x32_bf16 v[32:35], v[184:187], v[200:203], v[32:35]
	v_mfma_f32_16x16x32_bf16 v[20:23], v[176:179], v[208:211], v[20:23]
	v_mfma_f32_16x16x32_bf16 v[16:19], v[184:187], v[208:211], v[16:19]
	v_mfma_f32_16x16x32_bf16 v[4:7], v[176:179], v[220:223], v[4:7]
	v_mfma_f32_16x16x32_bf16 v[0:3], v[184:187], v[220:223], v[0:3]
	s_setprio 0
	s_barrier
	s_add_i32 s66, s66, 2
	s_add_u32 s30, s30, 0x100
	s_addc_u32 s31, s31, 0
	s_add_u32 s64, s64, 0x100
	s_addc_u32 s65, s65, 0
	s_cmp_gt_u32 s66, 13

.LBB0_438:
	s_ashr_i32 s23, s22, 31
	s_lshl_b64 s[24:25], s[22:23], 19
	s_add_u32 s24, s48, s24
	s_addc_u32 s25, s49, s25
	s_and_b64 s[26:27], s[4:5], exec
	s_cselect_b32 s23, s25, s31
	s_cselect_b32 s29, s24, s30
	s_ashr_i32 s21, s20, 31
	s_lshl_b64 s[26:27], s[20:21], 19
	s_add_u32 s26, s56, s26
	s_addc_u32 s27, s57, s27
	s_and_b64 s[54:55], s[4:5], exec
	s_cselect_b32 s21, s27, s53
	s_cselect_b32 s71, s26, s52
	s_add_u32 s30, s30, 0x40080
	s_addc_u32 s31, s31, 0
	s_add_u32 s73, s52, 0x100
	s_addc_u32 s74, s53, 0
	s_mov_b32 s76, -2
	s_waitcnt lgkmcnt(0)
	ds_read_b128 v[128:131], v181
	ds_read_b128 v[132:135], v181 offset:1024
	ds_read_b128 v[136:139], v181 offset:2048
	ds_read_b128 v[140:143], v181 offset:3072
	ds_read_b128 v[160:163], v182
	ds_read_b128 v[164:167], v182 offset:1024
	ds_read_b128 v[168:171], v182 offset:2048
	ds_read_b128 v[172:175], v182 offset:3072
	s_add_u32 s52, s30, 0xfffc0080
	s_addc_u32 s53, s31, -1
	s_cmp_eq_u32 s76, 12
	s_cselect_b32 s55, s23, s53
	s_cselect_b32 s54, s29, s52
	s_cselect_b32 s53, s21, s74
	s_cselect_b32 s52, s71, s73
	v_lshl_add_u64 v[212:213], s[30:31], 0, v[152:153]
	s_add_i32 m0, s59, 0xc000
	ds_read_b128 v[184:187], v183
	ds_read_b128 v[188:191], v183 offset:1024
	ds_read_b128 v[192:195], v183 offset:2048
	ds_read_b128 v[196:199], v183 offset:3072
	ds_read_b128 v[200:203], v183 offset:4096
	ds_read_b128 v[204:207], v183 offset:5120
	ds_read_b128 v[208:211], v183 offset:6144
	ds_read_b128 v[216:219], v183 offset:7168
	global_load_lds_dwordx4 v[212:213], off
	v_lshl_add_u64 v[212:213], s[30:31], 0, v[154:155]
	s_add_i32 m0, s59, 0xe000
	s_nop 0
	global_load_lds_dwordx4 v[212:213], off
	s_waitcnt vmcnt(8)
	s_waitcnt lgkmcnt(0)
	s_barrier
	s_setprio 1
	s_waitcnt lgkmcnt(0)
	v_mfma_f32_16x16x32_bf16 v[124:127], v[128:131], v[184:187], 0
	v_mfma_f32_16x16x32_bf16 v[120:123], v[136:139], v[184:187], 0
	v_mfma_f32_16x16x32_bf16 v[108:111], v[128:131], v[192:195], 0
	v_mfma_f32_16x16x32_bf16 v[104:107], v[136:139], v[192:195], 0
	v_mfma_f32_16x16x32_bf16 v[92:95], v[128:131], v[200:203], 0
	v_mfma_f32_16x16x32_bf16 v[88:91], v[136:139], v[200:203], 0
	v_mfma_f32_16x16x32_bf16 v[76:79], v[128:131], v[208:211], 0
	v_mfma_f32_16x16x32_bf16 v[72:75], v[136:139], v[208:211], 0
	v_mfma_f32_16x16x32_bf16 v[124:127], v[132:135], v[188:191], v[124:127]
	v_mfma_f32_16x16x32_bf16 v[120:123], v[140:143], v[188:191], v[120:123]
	v_mfma_f32_16x16x32_bf16 v[108:111], v[132:135], v[196:199], v[108:111]
	v_mfma_f32_16x16x32_bf16 v[104:107], v[140:143], v[196:199], v[104:107]
	v_mfma_f32_16x16x32_bf16 v[92:95], v[132:135], v[204:207], v[92:95]
	v_mfma_f32_16x16x32_bf16 v[88:91], v[140:143], v[204:207], v[88:91]
	v_mfma_f32_16x16x32_bf16 v[76:79], v[132:135], v[216:219], v[76:79]
	v_mfma_f32_16x16x32_bf16 v[72:75], v[140:143], v[216:219], v[72:75]
	s_setprio 0
	s_setprio 1
	v_mfma_f32_16x16x32_bf16 v[116:119], v[160:163], v[184:187], 0
	v_mfma_f32_16x16x32_bf16 v[112:115], v[168:171], v[184:187], 0
	v_mfma_f32_16x16x32_bf16 v[100:103], v[160:163], v[192:195], 0
	v_mfma_f32_16x16x32_bf16 v[96:99], v[168:171], v[192:195], 0
	v_mfma_f32_16x16x32_bf16 v[84:87], v[160:163], v[200:203], 0
	v_mfma_f32_16x16x32_bf16 v[80:83], v[168:171], v[200:203], 0
	v_mfma_f32_16x16x32_bf16 v[68:71], v[160:163], v[208:211], 0
	v_mfma_f32_16x16x32_bf16 v[64:67], v[168:171], v[208:211], 0
	v_mfma_f32_16x16x32_bf16 v[116:119], v[164:167], v[188:191], v[116:119]
	v_mfma_f32_16x16x32_bf16 v[112:115], v[172:175], v[188:191], v[112:115]
	v_mfma_f32_16x16x32_bf16 v[100:103], v[164:167], v[196:199], v[100:103]
	v_mfma_f32_16x16x32_bf16 v[96:99], v[172:175], v[196:199], v[96:99]
	v_mfma_f32_16x16x32_bf16 v[84:87], v[164:167], v[204:207], v[84:87]
	v_mfma_f32_16x16x32_bf16 v[80:83], v[172:175], v[204:207], v[80:83]
	v_mfma_f32_16x16x32_bf16 v[68:71], v[164:167], v[216:219], v[68:71]
	v_mfma_f32_16x16x32_bf16 v[64:67], v[172:175], v[216:219], v[64:67]
	s_setprio 0
	s_barrier
	s_add_i32 s72, s68, s58
	v_lshl_add_u64 v[212:213], s[52:53], 0, v[146:147]
	s_mov_b32 m0, s72
	ds_read_b128 v[184:187], v183 offset:16384
	ds_read_b128 v[188:191], v183 offset:17408
	ds_read_b128 v[192:195], v183 offset:18432
	ds_read_b128 v[196:199], v183 offset:19456
	ds_read_b128 v[200:203], v183 offset:20480
	ds_read_b128 v[204:207], v183 offset:21504
	ds_read_b128 v[208:211], v183 offset:22528
	ds_read_b128 v[216:219], v183 offset:23552
	global_load_lds_dwordx4 v[212:213], off
	s_add_i32 m0, s72, 0x2000
	s_add_u32 s78, s52, 0x40000
	v_lshl_add_u64 v[220:221], s[52:53], 0, v[150:151]
	s_addc_u32 s79, s53, 0
	s_add_i32 s72, s69, s58
	global_load_lds_dwordx4 v[220:221], off
	v_lshl_add_u64 v[222:223], s[78:79], 0, v[146:147]
	s_mov_b32 m0, s72
	v_lshl_add_u64 v[224:225], s[54:55], 0, v[148:149]
	global_load_lds_dwordx4 v[222:223], off
	v_lshl_add_u64 v[222:223], s[78:79], 0, v[150:151]
	s_add_i32 m0, s72, 0x2000
	s_nop 0
	global_load_lds_dwordx4 v[222:223], off
	v_lshl_add_u64 v[222:223], s[54:55], 0, v[144:145]
	s_mov_b32 m0, s59
	s_nop 0
	global_load_lds_dwordx4 v[222:223], off
	s_mov_b32 m0, s60
	s_nop 0
	global_load_lds_dwordx4 v[224:225], off
	s_waitcnt vmcnt(8)
	s_waitcnt lgkmcnt(0)
	s_barrier
	s_setprio 1
	s_waitcnt lgkmcnt(0)
	v_mfma_f32_16x16x32_bf16 v[60:63], v[128:131], v[184:187], 0
	v_mfma_f32_16x16x32_bf16 v[56:59], v[136:139], v[184:187], 0
	v_mfma_f32_16x16x32_bf16 v[44:47], v[128:131], v[192:195], 0
	v_mfma_f32_16x16x32_bf16 v[40:43], v[136:139], v[192:195], 0
	v_mfma_f32_16x16x32_bf16 v[28:31], v[128:131], v[200:203], 0
	v_mfma_f32_16x16x32_bf16 v[24:27], v[136:139], v[200:203], 0
	v_mfma_f32_16x16x32_bf16 v[12:15], v[128:131], v[208:211], 0
	v_mfma_f32_16x16x32_bf16 v[8:11], v[136:139], v[208:211], 0
	v_mfma_f32_16x16x32_bf16 v[60:63], v[132:135], v[188:191], v[60:63]
	v_mfma_f32_16x16x32_bf16 v[56:59], v[140:143], v[188:191], v[56:59]
	v_mfma_f32_16x16x32_bf16 v[44:47], v[132:135], v[196:199], v[44:47]
	v_mfma_f32_16x16x32_bf16 v[40:43], v[140:143], v[196:199], v[40:43]
	v_mfma_f32_16x16x32_bf16 v[28:31], v[132:135], v[204:207], v[28:31]
	v_mfma_f32_16x16x32_bf16 v[24:27], v[140:143], v[204:207], v[24:27]
	v_mfma_f32_16x16x32_bf16 v[12:15], v[132:135], v[216:219], v[12:15]
	v_mfma_f32_16x16x32_bf16 v[8:11], v[140:143], v[216:219], v[8:11]
	s_setprio 0
	s_setprio 1
	v_mfma_f32_16x16x32_bf16 v[52:55], v[160:163], v[184:187], 0
	v_mfma_f32_16x16x32_bf16 v[48:51], v[168:171], v[184:187], 0
	v_mfma_f32_16x16x32_bf16 v[36:39], v[160:163], v[192:195], 0
	v_mfma_f32_16x16x32_bf16 v[32:35], v[168:171], v[192:195], 0
	v_mfma_f32_16x16x32_bf16 v[20:23], v[160:163], v[200:203], 0
	v_mfma_f32_16x16x32_bf16 v[16:19], v[168:171], v[200:203], 0
	v_mfma_f32_16x16x32_bf16 v[4:7], v[160:163], v[208:211], 0
	v_mfma_f32_16x16x32_bf16 v[0:3], v[168:171], v[208:211], 0
	v_mfma_f32_16x16x32_bf16 v[52:55], v[164:167], v[188:191], v[52:55]
	v_mfma_f32_16x16x32_bf16 v[48:51], v[172:175], v[188:191], v[48:51]
	v_mfma_f32_16x16x32_bf16 v[36:39], v[164:167], v[196:199], v[36:39]
	v_mfma_f32_16x16x32_bf16 v[32:35], v[172:175], v[196:199], v[32:35]
	v_mfma_f32_16x16x32_bf16 v[20:23], v[164:167], v[204:207], v[20:23]
	v_mfma_f32_16x16x32_bf16 v[16:19], v[172:175], v[204:207], v[16:19]
	v_mfma_f32_16x16x32_bf16 v[4:7], v[164:167], v[216:219], v[4:7]
	v_mfma_f32_16x16x32_bf16 v[0:3], v[172:175], v[216:219], v[0:3]
	s_setprio 0
	s_barrier
	s_add_i32 s72, 0, 0x18000
	s_add_i32 s77, 0, 0x1c000
	v_add_u32_e32 v140, s72, v179
	v_add_u32_e32 v172, s77, v179
	ds_read_b128 v[128:131], v140
	ds_read_b128 v[132:135], v140 offset:1024
	ds_read_b128 v[136:139], v140 offset:2048
	ds_read_b128 v[140:143], v140 offset:3072
	ds_read_b128 v[160:163], v172
	ds_read_b128 v[164:167], v172 offset:1024
	ds_read_b128 v[168:171], v172 offset:2048
	ds_read_b128 v[172:175], v172 offset:3072
	s_add_u32 s54, s54, 0x40000
	s_addc_u32 s55, s55, 0
	s_mov_b32 m0, s61
	v_lshl_add_u64 v[226:227], s[54:55], 0, v[144:145]
	ds_read_b128 v[184:187], v183 offset:32768
	ds_read_b128 v[188:191], v183 offset:33792
	ds_read_b128 v[192:195], v183 offset:34816
	ds_read_b128 v[196:199], v183 offset:35840
	ds_read_b128 v[200:203], v183 offset:36864
	ds_read_b128 v[204:207], v183 offset:37888
	ds_read_b128 v[208:211], v183 offset:38912
	ds_read_b128 v[216:219], v183 offset:39936
	global_load_lds_dwordx4 v[226:227], off
	v_lshl_add_u64 v[226:227], s[54:55], 0, v[148:149]
	s_mov_b32 m0, s62
	s_nop 0
	global_load_lds_dwordx4 v[226:227], off
	s_waitcnt vmcnt(8)
	s_waitcnt lgkmcnt(0)
	s_barrier
	s_setprio 1
	s_waitcnt lgkmcnt(0)
	v_mfma_f32_16x16x32_bf16 v[124:127], v[128:131], v[184:187], v[124:127]
	v_mfma_f32_16x16x32_bf16 v[120:123], v[136:139], v[184:187], v[120:123]
	v_mfma_f32_16x16x32_bf16 v[108:111], v[128:131], v[192:195], v[108:111]
	v_mfma_f32_16x16x32_bf16 v[104:107], v[136:139], v[192:195], v[104:107]
	v_mfma_f32_16x16x32_bf16 v[92:95], v[128:131], v[200:203], v[92:95]
	v_mfma_f32_16x16x32_bf16 v[88:91], v[136:139], v[200:203], v[88:91]
	v_mfma_f32_16x16x32_bf16 v[76:79], v[128:131], v[208:211], v[76:79]
	v_mfma_f32_16x16x32_bf16 v[72:75], v[136:139], v[208:211], v[72:75]
	v_mfma_f32_16x16x32_bf16 v[124:127], v[132:135], v[188:191], v[124:127]
	v_mfma_f32_16x16x32_bf16 v[120:123], v[140:143], v[188:191], v[120:123]
	v_mfma_f32_16x16x32_bf16 v[108:111], v[132:135], v[196:199], v[108:111]
	v_mfma_f32_16x16x32_bf16 v[104:107], v[140:143], v[196:199], v[104:107]
	v_mfma_f32_16x16x32_bf16 v[92:95], v[132:135], v[204:207], v[92:95]
	v_mfma_f32_16x16x32_bf16 v[88:91], v[140:143], v[204:207], v[88:91]
	v_mfma_f32_16x16x32_bf16 v[76:79], v[132:135], v[216:219], v[76:79]
	v_mfma_f32_16x16x32_bf16 v[72:75], v[140:143], v[216:219], v[72:75]
	s_setprio 0
	s_setprio 1
	v_mfma_f32_16x16x32_bf16 v[116:119], v[160:163], v[184:187], v[116:119]
	v_mfma_f32_16x16x32_bf16 v[112:115], v[168:171], v[184:187], v[112:115]
	v_mfma_f32_16x16x32_bf16 v[100:103], v[160:163], v[192:195], v[100:103]
	v_mfma_f32_16x16x32_bf16 v[96:99], v[168:171], v[192:195], v[96:99]
	v_mfma_f32_16x16x32_bf16 v[84:87], v[160:163], v[200:203], v[84:87]
	v_mfma_f32_16x16x32_bf16 v[80:83], v[168:171], v[200:203], v[80:83]
	v_mfma_f32_16x16x32_bf16 v[68:71], v[160:163], v[208:211], v[68:71]
	v_mfma_f32_16x16x32_bf16 v[64:67], v[168:171], v[208:211], v[64:67]
	v_mfma_f32_16x16x32_bf16 v[116:119], v[164:167], v[188:191], v[116:119]
	v_mfma_f32_16x16x32_bf16 v[112:115], v[172:175], v[188:191], v[112:115]
	v_mfma_f32_16x16x32_bf16 v[100:103], v[164:167], v[196:199], v[100:103]
	v_mfma_f32_16x16x32_bf16 v[96:99], v[172:175], v[196:199], v[96:99]
	v_mfma_f32_16x16x32_bf16 v[84:87], v[164:167], v[204:207], v[84:87]
	v_mfma_f32_16x16x32_bf16 v[80:83], v[172:175], v[204:207], v[80:83]
	v_mfma_f32_16x16x32_bf16 v[68:71], v[164:167], v[216:219], v[68:71]
	v_mfma_f32_16x16x32_bf16 v[64:67], v[172:175], v[216:219], v[64:67]
	s_setprio 0
	s_barrier
	s_add_i32 s54, s72, s58
	v_lshl_add_u64 v[212:213], v[212:213], 0, s[12:13]
	s_mov_b32 m0, s54
	ds_read_b128 v[184:187], v183 offset:49152
	ds_read_b128 v[188:191], v183 offset:50176
	ds_read_b128 v[192:195], v183 offset:51200
	ds_read_b128 v[196:199], v183 offset:52224
	ds_read_b128 v[200:203], v183 offset:53248
	ds_read_b128 v[204:207], v183 offset:54272
	ds_read_b128 v[208:211], v183 offset:55296
	ds_read_b128 v[216:219], v183 offset:56320
	global_load_lds_dwordx4 v[212:213], off
	s_add_i32 m0, s54, 0x2000
	s_add_u32 s52, s52, 0x40080
	v_lshl_add_u64 v[212:213], v[220:221], 0, s[12:13]
	s_addc_u32 s53, s53, 0
	s_add_i32 s54, s77, s58
	global_load_lds_dwordx4 v[212:213], off
	v_lshl_add_u64 v[212:213], s[52:53], 0, v[146:147]
	s_mov_b32 m0, s54
	s_nop 0
	global_load_lds_dwordx4 v[212:213], off
	v_lshl_add_u64 v[212:213], s[52:53], 0, v[150:151]
	s_add_i32 m0, s54, 0x2000
	s_nop 0
	global_load_lds_dwordx4 v[212:213], off
	v_lshl_add_u64 v[212:213], v[222:223], 0, s[12:13]
	s_mov_b32 m0, s66
	s_nop 0
	global_load_lds_dwordx4 v[212:213], off
	v_lshl_add_u64 v[212:213], v[224:225], 0, s[12:13]
	s_mov_b32 m0, s67
	s_nop 0
	global_load_lds_dwordx4 v[212:213], off
	s_waitcnt vmcnt(8)
	s_waitcnt lgkmcnt(0)
	s_barrier
	s_setprio 1
	s_waitcnt lgkmcnt(0)
	v_mfma_f32_16x16x32_bf16 v[60:63], v[128:131], v[184:187], v[60:63]
	v_mfma_f32_16x16x32_bf16 v[56:59], v[136:139], v[184:187], v[56:59]
	v_mfma_f32_16x16x32_bf16 v[44:47], v[128:131], v[192:195], v[44:47]
	v_mfma_f32_16x16x32_bf16 v[40:43], v[136:139], v[192:195], v[40:43]
	v_mfma_f32_16x16x32_bf16 v[28:31], v[128:131], v[200:203], v[28:31]
	v_mfma_f32_16x16x32_bf16 v[24:27], v[136:139], v[200:203], v[24:27]
	v_mfma_f32_16x16x32_bf16 v[12:15], v[128:131], v[208:211], v[12:15]
	v_mfma_f32_16x16x32_bf16 v[8:11], v[136:139], v[208:211], v[8:11]
	v_mfma_f32_16x16x32_bf16 v[60:63], v[132:135], v[188:191], v[60:63]
	v_mfma_f32_16x16x32_bf16 v[56:59], v[140:143], v[188:191], v[56:59]
	v_mfma_f32_16x16x32_bf16 v[44:47], v[132:135], v[196:199], v[44:47]
	v_mfma_f32_16x16x32_bf16 v[40:43], v[140:143], v[196:199], v[40:43]
	v_mfma_f32_16x16x32_bf16 v[28:31], v[132:135], v[204:207], v[28:31]
	v_mfma_f32_16x16x32_bf16 v[24:27], v[140:143], v[204:207], v[24:27]
	v_mfma_f32_16x16x32_bf16 v[12:15], v[132:135], v[216:219], v[12:15]
	v_mfma_f32_16x16x32_bf16 v[8:11], v[140:143], v[216:219], v[8:11]
	s_setprio 0
	s_setprio 1
	v_mfma_f32_16x16x32_bf16 v[52:55], v[160:163], v[184:187], v[52:55]
	v_mfma_f32_16x16x32_bf16 v[48:51], v[168:171], v[184:187], v[48:51]
	v_mfma_f32_16x16x32_bf16 v[36:39], v[160:163], v[192:195], v[36:39]
	v_mfma_f32_16x16x32_bf16 v[32:35], v[168:171], v[192:195], v[32:35]
	v_mfma_f32_16x16x32_bf16 v[20:23], v[160:163], v[200:203], v[20:23]
	v_mfma_f32_16x16x32_bf16 v[16:19], v[168:171], v[200:203], v[16:19]
	v_mfma_f32_16x16x32_bf16 v[4:7], v[160:163], v[208:211], v[4:7]
	v_mfma_f32_16x16x32_bf16 v[0:3], v[168:171], v[208:211], v[0:3]
	v_mfma_f32_16x16x32_bf16 v[52:55], v[164:167], v[188:191], v[52:55]
	v_mfma_f32_16x16x32_bf16 v[48:51], v[172:175], v[188:191], v[48:51]
	v_mfma_f32_16x16x32_bf16 v[36:39], v[164:167], v[196:199], v[36:39]
	v_mfma_f32_16x16x32_bf16 v[32:35], v[172:175], v[196:199], v[32:35]
	v_mfma_f32_16x16x32_bf16 v[20:23], v[164:167], v[204:207], v[20:23]
	v_mfma_f32_16x16x32_bf16 v[16:19], v[172:175], v[204:207], v[16:19]
	v_mfma_f32_16x16x32_bf16 v[4:7], v[164:167], v[216:219], v[4:7]
	v_mfma_f32_16x16x32_bf16 v[0:3], v[172:175], v[216:219], v[0:3]
	s_setprio 0
	s_barrier
	s_add_i32 s76, s76, 2
	s_add_u32 s30, s30, 0x100
	s_addc_u32 s31, s31, 0
	s_add_u32 s73, s73, 0x100
	s_addc_u32 s74, s74, 0
	s_cmp_gt_u32 s76, 13

.LBB0_487:
	s_ashr_i32 s57, s56, 31
	s_lshl_b64 s[58:59], s[56:57], 19
	s_add_u32 s58, s46, s58
	s_addc_u32 s59, s47, s59
	s_and_b64 s[60:61], s[6:7], exec
	s_cselect_b32 s57, s59, s67
	s_cselect_b32 s63, s58, s66
	s_ashr_i32 s55, s54, 31
	s_lshl_b64 s[60:61], s[54:55], 19
	s_add_u32 s60, s73, s60
	s_addc_u32 s61, s74, s61
	s_and_b64 s[70:71], s[6:7], exec
	s_cselect_b32 s55, s61, s69
	s_cselect_b32 s65, s60, s68
	s_add_u32 s66, s66, 0x40080
	s_addc_u32 s67, s67, 0
	s_add_u32 s95, s68, 0x100
	s_addc_u32 s96, s69, 0
	s_mov_b32 s97, -2
	ds_read_b128 v[146:149], v220
	ds_read_b128 v[150:153], v220 offset:1024
	ds_read_b128 v[154:157], v220 offset:2048
	ds_read_b128 v[158:161], v220 offset:3072
	ds_read_b128 v[162:165], v221
	ds_read_b128 v[166:169], v221 offset:1024
	ds_read_b128 v[170:173], v221 offset:2048
	ds_read_b128 v[174:177], v221 offset:3072
	s_add_u32 s68, s66, 0xfffc0080
	s_addc_u32 s69, s67, -1
	s_cmp_eq_u32 s97, 12
	s_cselect_b32 s71, s57, s69
	s_cselect_b32 s70, s63, s68
	s_cselect_b32 s69, s55, s96
	s_cselect_b32 s68, s65, s95
	v_lshl_add_u64 v[210:211], s[66:67], 0, v[138:139]
	s_add_i32 m0, s77, 0xc000
	ds_read_b128 v[178:181], v222
	ds_read_b128 v[182:185], v222 offset:1024
	ds_read_b128 v[186:189], v222 offset:2048
	ds_read_b128 v[190:193], v222 offset:3072
	ds_read_b128 v[194:197], v222 offset:4096
	ds_read_b128 v[198:201], v222 offset:5120
	ds_read_b128 v[202:205], v222 offset:6144
	ds_read_b128 v[206:209], v222 offset:7168
	global_load_lds_dwordx4 v[210:211], off
	v_lshl_add_u64 v[210:211], s[66:67], 0, v[140:141]
	s_add_i32 m0, s77, 0xe000
	s_nop 0
	global_load_lds_dwordx4 v[210:211], off
	s_waitcnt vmcnt(8)
	s_waitcnt lgkmcnt(0)
	s_barrier
	s_setprio 1
	s_waitcnt lgkmcnt(0)
	v_mfma_f32_16x16x32_bf16 v[124:127], v[146:149], v[178:181], 0
	v_mfma_f32_16x16x32_bf16 v[60:63], v[154:157], v[178:181], 0
	v_mfma_f32_16x16x32_bf16 v[116:119], v[146:149], v[186:189], 0
	v_mfma_f32_16x16x32_bf16 v[52:55], v[154:157], v[186:189], 0
	v_mfma_f32_16x16x32_bf16 v[112:115], v[146:149], v[194:197], 0
	v_mfma_f32_16x16x32_bf16 v[48:51], v[154:157], v[194:197], 0
	v_mfma_f32_16x16x32_bf16 v[108:111], v[146:149], v[202:205], 0
	v_mfma_f32_16x16x32_bf16 v[40:43], v[154:157], v[202:205], 0
	v_mfma_f32_16x16x32_bf16 v[124:127], v[150:153], v[182:185], v[124:127]
	v_mfma_f32_16x16x32_bf16 v[60:63], v[158:161], v[182:185], v[60:63]
	v_mfma_f32_16x16x32_bf16 v[116:119], v[150:153], v[190:193], v[116:119]
	v_mfma_f32_16x16x32_bf16 v[52:55], v[158:161], v[190:193], v[52:55]
	v_mfma_f32_16x16x32_bf16 v[112:115], v[150:153], v[198:201], v[112:115]
	v_mfma_f32_16x16x32_bf16 v[48:51], v[158:161], v[198:201], v[48:51]
	v_mfma_f32_16x16x32_bf16 v[108:111], v[150:153], v[206:209], v[108:111]
	v_mfma_f32_16x16x32_bf16 v[40:43], v[158:161], v[206:209], v[40:43]
	s_setprio 0
	s_setprio 1
	v_mfma_f32_16x16x32_bf16 v[120:123], v[162:165], v[178:181], 0
	v_mfma_f32_16x16x32_bf16 v[56:59], v[170:173], v[178:181], 0
	v_mfma_f32_16x16x32_bf16 v[104:107], v[162:165], v[186:189], 0
	v_mfma_f32_16x16x32_bf16 v[44:47], v[170:173], v[186:189], 0
	v_mfma_f32_16x16x32_bf16 v[100:103], v[162:165], v[194:197], 0
	v_mfma_f32_16x16x32_bf16 v[36:39], v[170:173], v[194:197], 0
	v_mfma_f32_16x16x32_bf16 v[96:99], v[162:165], v[202:205], 0
	v_mfma_f32_16x16x32_bf16 v[32:35], v[170:173], v[202:205], 0
	v_mfma_f32_16x16x32_bf16 v[120:123], v[166:169], v[182:185], v[120:123]
	v_mfma_f32_16x16x32_bf16 v[56:59], v[174:177], v[182:185], v[56:59]
	v_mfma_f32_16x16x32_bf16 v[104:107], v[166:169], v[190:193], v[104:107]
	v_mfma_f32_16x16x32_bf16 v[44:47], v[174:177], v[190:193], v[44:47]
	v_mfma_f32_16x16x32_bf16 v[100:103], v[166:169], v[198:201], v[100:103]
	v_mfma_f32_16x16x32_bf16 v[36:39], v[174:177], v[198:201], v[36:39]
	v_mfma_f32_16x16x32_bf16 v[96:99], v[166:169], v[206:209], v[96:99]
	v_mfma_f32_16x16x32_bf16 v[32:35], v[174:177], v[206:209], v[32:35]
	s_setprio 0
	s_barrier
	s_add_i32 s72, s91, s76
	v_lshl_add_u64 v[210:211], s[68:69], 0, v[128:129]
	s_mov_b32 m0, s72
	ds_read_b128 v[178:181], v222 offset:16384
	ds_read_b128 v[182:185], v222 offset:17408
	ds_read_b128 v[186:189], v222 offset:18432
	ds_read_b128 v[190:193], v222 offset:19456
	ds_read_b128 v[194:197], v222 offset:20480
	ds_read_b128 v[198:201], v222 offset:21504
	ds_read_b128 v[202:205], v222 offset:22528
	ds_read_b128 v[206:209], v222 offset:23552
	global_load_lds_dwordx4 v[210:211], off
	s_add_i32 m0, s72, 0x2000
	s_add_u32 vcc_lo, s68, 0x40000
	v_lshl_add_u64 v[212:213], s[68:69], 0, v[130:131]
	s_addc_u32 vcc_hi, s69, 0
	s_add_i32 s72, s92, s76
	global_load_lds_dwordx4 v[212:213], off
	v_lshl_add_u64 v[224:225], vcc, 0, v[128:129]
	s_mov_b32 m0, s72
	v_lshl_add_u64 v[226:227], s[70:71], 0, v[130:131]
	global_load_lds_dwordx4 v[224:225], off
	v_lshl_add_u64 v[224:225], vcc, 0, v[130:131]
	s_add_i32 m0, s72, 0x2000
	s_nop 0
	global_load_lds_dwordx4 v[224:225], off
	v_lshl_add_u64 v[224:225], s[70:71], 0, v[128:129]
	s_mov_b32 m0, s77
	s_nop 0
	global_load_lds_dwordx4 v[224:225], off
	s_mov_b32 m0, s78
	s_nop 0
	global_load_lds_dwordx4 v[226:227], off
	s_waitcnt vmcnt(8)
	s_waitcnt lgkmcnt(0)
	s_barrier
	s_setprio 1
	s_waitcnt lgkmcnt(0)
	v_mfma_f32_16x16x32_bf16 v[92:95], v[146:149], v[178:181], 0
	v_mfma_f32_16x16x32_bf16 v[28:31], v[154:157], v[178:181], 0
	v_mfma_f32_16x16x32_bf16 v[84:87], v[146:149], v[186:189], 0
	v_mfma_f32_16x16x32_bf16 v[20:23], v[154:157], v[186:189], 0
	v_mfma_f32_16x16x32_bf16 v[80:83], v[146:149], v[194:197], 0
	v_mfma_f32_16x16x32_bf16 v[16:19], v[154:157], v[194:197], 0
	v_mfma_f32_16x16x32_bf16 v[76:79], v[146:149], v[202:205], 0
	v_mfma_f32_16x16x32_bf16 v[8:11], v[154:157], v[202:205], 0
	v_mfma_f32_16x16x32_bf16 v[92:95], v[150:153], v[182:185], v[92:95]
	v_mfma_f32_16x16x32_bf16 v[28:31], v[158:161], v[182:185], v[28:31]
	v_mfma_f32_16x16x32_bf16 v[84:87], v[150:153], v[190:193], v[84:87]
	v_mfma_f32_16x16x32_bf16 v[20:23], v[158:161], v[190:193], v[20:23]
	v_mfma_f32_16x16x32_bf16 v[80:83], v[150:153], v[198:201], v[80:83]
	v_mfma_f32_16x16x32_bf16 v[16:19], v[158:161], v[198:201], v[16:19]
	v_mfma_f32_16x16x32_bf16 v[76:79], v[150:153], v[206:209], v[76:79]
	v_mfma_f32_16x16x32_bf16 v[8:11], v[158:161], v[206:209], v[8:11]
	s_setprio 0
	s_setprio 1
	v_mfma_f32_16x16x32_bf16 v[88:91], v[162:165], v[178:181], 0
	v_mfma_f32_16x16x32_bf16 v[24:27], v[170:173], v[178:181], 0
	v_mfma_f32_16x16x32_bf16 v[72:75], v[162:165], v[186:189], 0
	v_mfma_f32_16x16x32_bf16 v[12:15], v[170:173], v[186:189], 0
	v_mfma_f32_16x16x32_bf16 v[68:71], v[162:165], v[194:197], 0
	v_mfma_f32_16x16x32_bf16 v[4:7], v[170:173], v[194:197], 0
	v_mfma_f32_16x16x32_bf16 v[64:67], v[162:165], v[202:205], 0
	v_mfma_f32_16x16x32_bf16 v[0:3], v[170:173], v[202:205], 0
	v_mfma_f32_16x16x32_bf16 v[88:91], v[166:169], v[182:185], v[88:91]
	v_mfma_f32_16x16x32_bf16 v[24:27], v[174:177], v[182:185], v[24:27]
	v_mfma_f32_16x16x32_bf16 v[72:75], v[166:169], v[190:193], v[72:75]
	v_mfma_f32_16x16x32_bf16 v[12:15], v[174:177], v[190:193], v[12:15]
	v_mfma_f32_16x16x32_bf16 v[68:71], v[166:169], v[198:201], v[68:71]
	v_mfma_f32_16x16x32_bf16 v[4:7], v[174:177], v[198:201], v[4:7]
	v_mfma_f32_16x16x32_bf16 v[64:67], v[166:169], v[206:209], v[64:67]
	v_mfma_f32_16x16x32_bf16 v[0:3], v[174:177], v[206:209], v[0:3]
	s_setprio 0
	s_barrier
	s_add_i32 s72, 0, 0x18000
	s_add_i32 vcc_lo, 0, 0x1c000
	v_add_u32_e32 v158, s72, v216
	v_add_u32_e32 v174, vcc_lo, v216
	ds_read_b128 v[146:149], v158
	ds_read_b128 v[150:153], v158 offset:1024
	ds_read_b128 v[154:157], v158 offset:2048
	ds_read_b128 v[158:161], v158 offset:3072
	ds_read_b128 v[162:165], v174
	ds_read_b128 v[166:169], v174 offset:1024
	ds_read_b128 v[170:173], v174 offset:2048
	ds_read_b128 v[174:177], v174 offset:3072
	s_add_u32 s70, s70, 0x40000
	s_addc_u32 s71, s71, 0
	s_mov_b32 m0, s79
	v_lshl_add_u64 v[228:229], s[70:71], 0, v[128:129]
	ds_read_b128 v[178:181], v222 offset:32768
	ds_read_b128 v[182:185], v222 offset:33792
	ds_read_b128 v[186:189], v222 offset:34816
	ds_read_b128 v[190:193], v222 offset:35840
	ds_read_b128 v[194:197], v222 offset:36864
	ds_read_b128 v[198:201], v222 offset:37888
	ds_read_b128 v[202:205], v222 offset:38912
	ds_read_b128 v[206:209], v222 offset:39936
	global_load_lds_dwordx4 v[228:229], off
	v_lshl_add_u64 v[228:229], s[70:71], 0, v[130:131]
	s_mov_b32 m0, s80
	s_nop 0
	global_load_lds_dwordx4 v[228:229], off
	s_waitcnt vmcnt(8)
	s_waitcnt lgkmcnt(0)
	s_barrier
	s_setprio 1
	s_waitcnt lgkmcnt(0)
	v_mfma_f32_16x16x32_bf16 v[124:127], v[146:149], v[178:181], v[124:127]
	v_mfma_f32_16x16x32_bf16 v[60:63], v[154:157], v[178:181], v[60:63]
	v_mfma_f32_16x16x32_bf16 v[116:119], v[146:149], v[186:189], v[116:119]
	v_mfma_f32_16x16x32_bf16 v[52:55], v[154:157], v[186:189], v[52:55]
	v_mfma_f32_16x16x32_bf16 v[112:115], v[146:149], v[194:197], v[112:115]
	v_mfma_f32_16x16x32_bf16 v[48:51], v[154:157], v[194:197], v[48:51]
	v_mfma_f32_16x16x32_bf16 v[108:111], v[146:149], v[202:205], v[108:111]
	v_mfma_f32_16x16x32_bf16 v[40:43], v[154:157], v[202:205], v[40:43]
	v_mfma_f32_16x16x32_bf16 v[124:127], v[150:153], v[182:185], v[124:127]
	v_mfma_f32_16x16x32_bf16 v[60:63], v[158:161], v[182:185], v[60:63]
	v_mfma_f32_16x16x32_bf16 v[116:119], v[150:153], v[190:193], v[116:119]
	v_mfma_f32_16x16x32_bf16 v[52:55], v[158:161], v[190:193], v[52:55]
	v_mfma_f32_16x16x32_bf16 v[112:115], v[150:153], v[198:201], v[112:115]
	v_mfma_f32_16x16x32_bf16 v[48:51], v[158:161], v[198:201], v[48:51]
	v_mfma_f32_16x16x32_bf16 v[108:111], v[150:153], v[206:209], v[108:111]
	v_mfma_f32_16x16x32_bf16 v[40:43], v[158:161], v[206:209], v[40:43]
	s_setprio 0
	s_setprio 1
	v_mfma_f32_16x16x32_bf16 v[120:123], v[162:165], v[178:181], v[120:123]
	v_mfma_f32_16x16x32_bf16 v[56:59], v[170:173], v[178:181], v[56:59]
	v_mfma_f32_16x16x32_bf16 v[104:107], v[162:165], v[186:189], v[104:107]
	v_mfma_f32_16x16x32_bf16 v[44:47], v[170:173], v[186:189], v[44:47]
	v_mfma_f32_16x16x32_bf16 v[100:103], v[162:165], v[194:197], v[100:103]
	v_mfma_f32_16x16x32_bf16 v[36:39], v[170:173], v[194:197], v[36:39]
	v_mfma_f32_16x16x32_bf16 v[96:99], v[162:165], v[202:205], v[96:99]
	v_mfma_f32_16x16x32_bf16 v[32:35], v[170:173], v[202:205], v[32:35]
	v_mfma_f32_16x16x32_bf16 v[120:123], v[166:169], v[182:185], v[120:123]
	v_mfma_f32_16x16x32_bf16 v[56:59], v[174:177], v[182:185], v[56:59]
	v_mfma_f32_16x16x32_bf16 v[104:107], v[166:169], v[190:193], v[104:107]
	v_mfma_f32_16x16x32_bf16 v[44:47], v[174:177], v[190:193], v[44:47]
	v_mfma_f32_16x16x32_bf16 v[100:103], v[166:169], v[198:201], v[100:103]
	v_mfma_f32_16x16x32_bf16 v[36:39], v[174:177], v[198:201], v[36:39]
	v_mfma_f32_16x16x32_bf16 v[96:99], v[166:169], v[206:209], v[96:99]
	v_mfma_f32_16x16x32_bf16 v[32:35], v[174:177], v[206:209], v[32:35]
	s_setprio 0
	s_barrier
	s_add_i32 s70, s72, s76
	v_lshl_add_u64 v[210:211], v[210:211], 0, s[20:21]
	s_mov_b32 m0, s70
	ds_read_b128 v[178:181], v222 offset:49152
	ds_read_b128 v[182:185], v222 offset:50176
	ds_read_b128 v[186:189], v222 offset:51200
	ds_read_b128 v[190:193], v222 offset:52224
	ds_read_b128 v[194:197], v222 offset:53248
	ds_read_b128 v[198:201], v222 offset:54272
	ds_read_b128 v[202:205], v222 offset:55296
	ds_read_b128 v[206:209], v222 offset:56320
	global_load_lds_dwordx4 v[210:211], off
	s_add_i32 m0, s70, 0x2000
	s_add_u32 s68, s68, 0x40080
	v_lshl_add_u64 v[210:211], v[212:213], 0, s[20:21]
	s_addc_u32 s69, s69, 0
	s_add_i32 s70, vcc_lo, s76
	global_load_lds_dwordx4 v[210:211], off
	v_lshl_add_u64 v[210:211], s[68:69], 0, v[128:129]
	s_mov_b32 m0, s70
	s_nop 0
	global_load_lds_dwordx4 v[210:211], off
	v_lshl_add_u64 v[210:211], s[68:69], 0, v[130:131]
	s_add_i32 m0, s70, 0x2000
	s_nop 0
	global_load_lds_dwordx4 v[210:211], off
	v_lshl_add_u64 v[210:211], v[224:225], 0, s[20:21]
	s_mov_b32 m0, s88
	s_nop 0
	global_load_lds_dwordx4 v[210:211], off
	v_lshl_add_u64 v[210:211], v[226:227], 0, s[20:21]
	s_mov_b32 m0, s89
	s_nop 0
	global_load_lds_dwordx4 v[210:211], off
	s_waitcnt vmcnt(8)
	s_waitcnt lgkmcnt(0)
	s_barrier
	s_setprio 1
	s_waitcnt lgkmcnt(0)
	v_mfma_f32_16x16x32_bf16 v[92:95], v[146:149], v[178:181], v[92:95]
	v_mfma_f32_16x16x32_bf16 v[28:31], v[154:157], v[178:181], v[28:31]
	v_mfma_f32_16x16x32_bf16 v[84:87], v[146:149], v[186:189], v[84:87]
	v_mfma_f32_16x16x32_bf16 v[20:23], v[154:157], v[186:189], v[20:23]
	v_mfma_f32_16x16x32_bf16 v[80:83], v[146:149], v[194:197], v[80:83]
	v_mfma_f32_16x16x32_bf16 v[16:19], v[154:157], v[194:197], v[16:19]
	v_mfma_f32_16x16x32_bf16 v[76:79], v[146:149], v[202:205], v[76:79]
	v_mfma_f32_16x16x32_bf16 v[8:11], v[154:157], v[202:205], v[8:11]
	v_mfma_f32_16x16x32_bf16 v[92:95], v[150:153], v[182:185], v[92:95]
	v_mfma_f32_16x16x32_bf16 v[28:31], v[158:161], v[182:185], v[28:31]
	v_mfma_f32_16x16x32_bf16 v[84:87], v[150:153], v[190:193], v[84:87]
	v_mfma_f32_16x16x32_bf16 v[20:23], v[158:161], v[190:193], v[20:23]
	v_mfma_f32_16x16x32_bf16 v[80:83], v[150:153], v[198:201], v[80:83]
	v_mfma_f32_16x16x32_bf16 v[16:19], v[158:161], v[198:201], v[16:19]
	v_mfma_f32_16x16x32_bf16 v[76:79], v[150:153], v[206:209], v[76:79]
	v_mfma_f32_16x16x32_bf16 v[8:11], v[158:161], v[206:209], v[8:11]
	s_setprio 0
	s_setprio 1
	v_mfma_f32_16x16x32_bf16 v[88:91], v[162:165], v[178:181], v[88:91]
	v_mfma_f32_16x16x32_bf16 v[24:27], v[170:173], v[178:181], v[24:27]
	v_mfma_f32_16x16x32_bf16 v[72:75], v[162:165], v[186:189], v[72:75]
	v_mfma_f32_16x16x32_bf16 v[12:15], v[170:173], v[186:189], v[12:15]
	v_mfma_f32_16x16x32_bf16 v[68:71], v[162:165], v[194:197], v[68:71]
	v_mfma_f32_16x16x32_bf16 v[4:7], v[170:173], v[194:197], v[4:7]
	v_mfma_f32_16x16x32_bf16 v[64:67], v[162:165], v[202:205], v[64:67]
	v_mfma_f32_16x16x32_bf16 v[0:3], v[170:173], v[202:205], v[0:3]
	v_mfma_f32_16x16x32_bf16 v[88:91], v[166:169], v[182:185], v[88:91]
	v_mfma_f32_16x16x32_bf16 v[24:27], v[174:177], v[182:185], v[24:27]
	v_mfma_f32_16x16x32_bf16 v[72:75], v[166:169], v[190:193], v[72:75]
	v_mfma_f32_16x16x32_bf16 v[12:15], v[174:177], v[190:193], v[12:15]
	v_mfma_f32_16x16x32_bf16 v[68:71], v[166:169], v[198:201], v[68:71]
	v_mfma_f32_16x16x32_bf16 v[4:7], v[174:177], v[198:201], v[4:7]
	v_mfma_f32_16x16x32_bf16 v[64:67], v[166:169], v[206:209], v[64:67]
	v_mfma_f32_16x16x32_bf16 v[0:3], v[174:177], v[206:209], v[0:3]
	s_setprio 0
	s_barrier
	s_add_i32 s97, s97, 2
	s_add_u32 s66, s66, 0x100
	s_addc_u32 s67, s67, 0
	s_add_u32 s95, s95, 0x100
	s_addc_u32 s96, s96, 0
	s_cmp_gt_u32 s97, 13

.LBB0_657:
	s_add_u32 s12, s26, 0x100
	s_addc_u32 s74, s27, 0
	s_mov_b32 s72, -2
	s_waitcnt lgkmcnt(0)
	ds_read_b128 v[128:131], v177
	ds_read_b128 v[132:135], v177 offset:1024
	ds_read_b128 v[136:139], v177 offset:2048
	ds_read_b128 v[140:143], v177 offset:3072
	ds_read_b128 v[158:161], v178
	ds_read_b128 v[162:165], v178 offset:1024
	ds_read_b128 v[166:169], v178 offset:2048
	ds_read_b128 v[180:183], v178 offset:3072
	s_add_u32 s26, s24, 0x100
	s_addc_u32 s27, s25, 0
	s_cmp_eq_u32 s72, 40
	s_cselect_b32 s31, s7, s27
	s_cselect_b32 s30, s6, s26
	s_cselect_b32 s29, s23, s74
	s_cselect_b32 s28, s22, s12
	v_lshl_add_u64 v[170:171], s[24:25], 0, v[152:153]
	s_add_i32 m0, s57, 0xc000
	ds_read_b128 v[184:187], v179
	ds_read_b128 v[188:191], v179 offset:1024
	ds_read_b128 v[192:195], v179 offset:2048
	ds_read_b128 v[196:199], v179 offset:3072
	ds_read_b128 v[200:203], v179 offset:4096
	ds_read_b128 v[204:207], v179 offset:5120
	ds_read_b128 v[208:211], v179 offset:6144
	ds_read_b128 v[216:219], v179 offset:7168
	global_load_lds_dwordx4 v[170:171], off
	v_lshl_add_u64 v[170:171], s[24:25], 0, v[154:155]
	s_add_i32 m0, s57, 0xe000
	s_nop 0
	global_load_lds_dwordx4 v[170:171], off
	s_waitcnt vmcnt(8)
	s_waitcnt lgkmcnt(0)
	s_barrier
	s_setprio 1
	s_waitcnt lgkmcnt(0)
	v_mfma_f32_16x16x32_bf16 v[124:127], v[128:131], v[184:187], 0
	v_mfma_f32_16x16x32_bf16 v[120:123], v[136:139], v[184:187], 0
	v_mfma_f32_16x16x32_bf16 v[108:111], v[128:131], v[192:195], 0
	v_mfma_f32_16x16x32_bf16 v[104:107], v[136:139], v[192:195], 0
	v_mfma_f32_16x16x32_bf16 v[92:95], v[128:131], v[200:203], 0
	v_mfma_f32_16x16x32_bf16 v[88:91], v[136:139], v[200:203], 0
	v_mfma_f32_16x16x32_bf16 v[76:79], v[128:131], v[208:211], 0
	v_mfma_f32_16x16x32_bf16 v[72:75], v[136:139], v[208:211], 0
	v_mfma_f32_16x16x32_bf16 v[124:127], v[132:135], v[188:191], v[124:127]
	v_mfma_f32_16x16x32_bf16 v[120:123], v[140:143], v[188:191], v[120:123]
	v_mfma_f32_16x16x32_bf16 v[108:111], v[132:135], v[196:199], v[108:111]
	v_mfma_f32_16x16x32_bf16 v[104:107], v[140:143], v[196:199], v[104:107]
	v_mfma_f32_16x16x32_bf16 v[92:95], v[132:135], v[204:207], v[92:95]
	v_mfma_f32_16x16x32_bf16 v[88:91], v[140:143], v[204:207], v[88:91]
	v_mfma_f32_16x16x32_bf16 v[76:79], v[132:135], v[216:219], v[76:79]
	v_mfma_f32_16x16x32_bf16 v[72:75], v[140:143], v[216:219], v[72:75]
	s_setprio 0
	s_setprio 1
	v_mfma_f32_16x16x32_bf16 v[116:119], v[158:161], v[184:187], 0
	v_mfma_f32_16x16x32_bf16 v[112:115], v[166:169], v[184:187], 0
	v_mfma_f32_16x16x32_bf16 v[100:103], v[158:161], v[192:195], 0
	v_mfma_f32_16x16x32_bf16 v[96:99], v[166:169], v[192:195], 0
	v_mfma_f32_16x16x32_bf16 v[84:87], v[158:161], v[200:203], 0
	v_mfma_f32_16x16x32_bf16 v[80:83], v[166:169], v[200:203], 0
	v_mfma_f32_16x16x32_bf16 v[68:71], v[158:161], v[208:211], 0
	v_mfma_f32_16x16x32_bf16 v[64:67], v[166:169], v[208:211], 0
	v_mfma_f32_16x16x32_bf16 v[116:119], v[162:165], v[188:191], v[116:119]
	v_mfma_f32_16x16x32_bf16 v[112:115], v[180:183], v[188:191], v[112:115]
	v_mfma_f32_16x16x32_bf16 v[100:103], v[162:165], v[196:199], v[100:103]
	v_mfma_f32_16x16x32_bf16 v[96:99], v[180:183], v[196:199], v[96:99]
	v_mfma_f32_16x16x32_bf16 v[84:87], v[162:165], v[204:207], v[84:87]
	v_mfma_f32_16x16x32_bf16 v[80:83], v[180:183], v[204:207], v[80:83]
	v_mfma_f32_16x16x32_bf16 v[68:71], v[162:165], v[216:219], v[68:71]
	v_mfma_f32_16x16x32_bf16 v[64:67], v[180:183], v[216:219], v[64:67]
	s_setprio 0
	s_barrier
	s_add_i32 s24, s66, s56
	v_lshl_add_u64 v[170:171], s[28:29], 0, v[146:147]
	s_mov_b32 m0, s24
	ds_read_b128 v[184:187], v179 offset:16384
	ds_read_b128 v[188:191], v179 offset:17408
	ds_read_b128 v[192:195], v179 offset:18432
	ds_read_b128 v[196:199], v179 offset:19456
	ds_read_b128 v[200:203], v179 offset:20480
	ds_read_b128 v[204:207], v179 offset:21504
	ds_read_b128 v[208:211], v179 offset:22528
	ds_read_b128 v[216:219], v179 offset:23552
	global_load_lds_dwordx4 v[170:171], off
	s_add_i32 m0, s24, 0x2000
	s_add_u32 s24, s28, 0xb0000
	v_lshl_add_u64 v[212:213], s[28:29], 0, v[150:151]
	s_addc_u32 s25, s29, 0
	s_add_i32 s76, s67, s56
	global_load_lds_dwordx4 v[212:213], off
	v_lshl_add_u64 v[220:221], s[24:25], 0, v[146:147]
	s_mov_b32 m0, s76
	v_lshl_add_u64 v[222:223], s[30:31], 0, v[148:149]
	global_load_lds_dwordx4 v[220:221], off
	v_lshl_add_u64 v[220:221], s[24:25], 0, v[150:151]
	s_add_i32 m0, s76, 0x2000
	s_nop 0
	global_load_lds_dwordx4 v[220:221], off
	v_lshl_add_u64 v[220:221], s[30:31], 0, v[144:145]
	s_mov_b32 m0, s57
	s_nop 0
	global_load_lds_dwordx4 v[220:221], off
	s_mov_b32 m0, s58
	s_nop 0
	global_load_lds_dwordx4 v[222:223], off
	s_waitcnt vmcnt(8)
	s_waitcnt lgkmcnt(0)
	s_barrier
	s_setprio 1
	s_waitcnt lgkmcnt(0)
	v_mfma_f32_16x16x32_bf16 v[60:63], v[128:131], v[184:187], 0
	v_mfma_f32_16x16x32_bf16 v[56:59], v[136:139], v[184:187], 0
	v_mfma_f32_16x16x32_bf16 v[44:47], v[128:131], v[192:195], 0
	v_mfma_f32_16x16x32_bf16 v[40:43], v[136:139], v[192:195], 0
	v_mfma_f32_16x16x32_bf16 v[28:31], v[128:131], v[200:203], 0
	v_mfma_f32_16x16x32_bf16 v[24:27], v[136:139], v[200:203], 0
	v_mfma_f32_16x16x32_bf16 v[12:15], v[128:131], v[208:211], 0
	v_mfma_f32_16x16x32_bf16 v[8:11], v[136:139], v[208:211], 0
	v_mfma_f32_16x16x32_bf16 v[60:63], v[132:135], v[188:191], v[60:63]
	v_mfma_f32_16x16x32_bf16 v[56:59], v[140:143], v[188:191], v[56:59]
	v_mfma_f32_16x16x32_bf16 v[44:47], v[132:135], v[196:199], v[44:47]
	v_mfma_f32_16x16x32_bf16 v[40:43], v[140:143], v[196:199], v[40:43]
	v_mfma_f32_16x16x32_bf16 v[28:31], v[132:135], v[204:207], v[28:31]
	v_mfma_f32_16x16x32_bf16 v[24:27], v[140:143], v[204:207], v[24:27]
	v_mfma_f32_16x16x32_bf16 v[12:15], v[132:135], v[216:219], v[12:15]
	v_mfma_f32_16x16x32_bf16 v[8:11], v[140:143], v[216:219], v[8:11]
	s_setprio 0
	s_setprio 1
	v_mfma_f32_16x16x32_bf16 v[52:55], v[158:161], v[184:187], 0
	v_mfma_f32_16x16x32_bf16 v[48:51], v[166:169], v[184:187], 0
	v_mfma_f32_16x16x32_bf16 v[36:39], v[158:161], v[192:195], 0
	v_mfma_f32_16x16x32_bf16 v[32:35], v[166:169], v[192:195], 0
	v_mfma_f32_16x16x32_bf16 v[20:23], v[158:161], v[200:203], 0
	v_mfma_f32_16x16x32_bf16 v[16:19], v[166:169], v[200:203], 0
	v_mfma_f32_16x16x32_bf16 v[4:7], v[158:161], v[208:211], 0
	v_mfma_f32_16x16x32_bf16 v[0:3], v[166:169], v[208:211], 0
	v_mfma_f32_16x16x32_bf16 v[52:55], v[162:165], v[188:191], v[52:55]
	v_mfma_f32_16x16x32_bf16 v[48:51], v[180:183], v[188:191], v[48:51]
	v_mfma_f32_16x16x32_bf16 v[36:39], v[162:165], v[196:199], v[36:39]
	v_mfma_f32_16x16x32_bf16 v[32:35], v[180:183], v[196:199], v[32:35]
	v_mfma_f32_16x16x32_bf16 v[20:23], v[162:165], v[204:207], v[20:23]
	v_mfma_f32_16x16x32_bf16 v[16:19], v[180:183], v[204:207], v[16:19]
	v_mfma_f32_16x16x32_bf16 v[4:7], v[162:165], v[216:219], v[4:7]
	v_mfma_f32_16x16x32_bf16 v[0:3], v[180:183], v[216:219], v[0:3]
	s_setprio 0
	s_barrier
	s_add_i32 s76, 0, 0x18000
	s_add_i32 s77, 0, 0x1c000
	v_add_u32_e32 v140, s76, v175
	v_add_u32_e32 v180, s77, v175
	ds_read_b128 v[128:131], v140
	ds_read_b128 v[132:135], v140 offset:1024
	ds_read_b128 v[136:139], v140 offset:2048
	ds_read_b128 v[140:143], v140 offset:3072
	ds_read_b128 v[158:161], v180
	ds_read_b128 v[162:165], v180 offset:1024
	ds_read_b128 v[166:169], v180 offset:2048
	ds_read_b128 v[180:183], v180 offset:3072
	s_add_u32 s24, s30, 0xb0000
	s_addc_u32 s25, s31, 0
	s_mov_b32 m0, s59
	v_lshl_add_u64 v[224:225], s[24:25], 0, v[144:145]
	ds_read_b128 v[184:187], v179 offset:32768
	ds_read_b128 v[188:191], v179 offset:33792
	ds_read_b128 v[192:195], v179 offset:34816
	ds_read_b128 v[196:199], v179 offset:35840
	ds_read_b128 v[200:203], v179 offset:36864
	ds_read_b128 v[204:207], v179 offset:37888
	ds_read_b128 v[208:211], v179 offset:38912
	ds_read_b128 v[216:219], v179 offset:39936
	global_load_lds_dwordx4 v[224:225], off
	v_lshl_add_u64 v[224:225], s[24:25], 0, v[148:149]
	s_mov_b32 m0, s60
	s_nop 0
	global_load_lds_dwordx4 v[224:225], off
	s_waitcnt vmcnt(8)
	s_waitcnt lgkmcnt(0)
	s_barrier
	s_setprio 1
	s_waitcnt lgkmcnt(0)
	v_mfma_f32_16x16x32_bf16 v[124:127], v[128:131], v[184:187], v[124:127]
	v_mfma_f32_16x16x32_bf16 v[120:123], v[136:139], v[184:187], v[120:123]
	v_mfma_f32_16x16x32_bf16 v[108:111], v[128:131], v[192:195], v[108:111]
	v_mfma_f32_16x16x32_bf16 v[104:107], v[136:139], v[192:195], v[104:107]
	v_mfma_f32_16x16x32_bf16 v[92:95], v[128:131], v[200:203], v[92:95]
	v_mfma_f32_16x16x32_bf16 v[88:91], v[136:139], v[200:203], v[88:91]
	v_mfma_f32_16x16x32_bf16 v[76:79], v[128:131], v[208:211], v[76:79]
	v_mfma_f32_16x16x32_bf16 v[72:75], v[136:139], v[208:211], v[72:75]
	v_mfma_f32_16x16x32_bf16 v[124:127], v[132:135], v[188:191], v[124:127]
	v_mfma_f32_16x16x32_bf16 v[120:123], v[140:143], v[188:191], v[120:123]
	v_mfma_f32_16x16x32_bf16 v[108:111], v[132:135], v[196:199], v[108:111]
	v_mfma_f32_16x16x32_bf16 v[104:107], v[140:143], v[196:199], v[104:107]
	v_mfma_f32_16x16x32_bf16 v[92:95], v[132:135], v[204:207], v[92:95]
	v_mfma_f32_16x16x32_bf16 v[88:91], v[140:143], v[204:207], v[88:91]
	v_mfma_f32_16x16x32_bf16 v[76:79], v[132:135], v[216:219], v[76:79]
	v_mfma_f32_16x16x32_bf16 v[72:75], v[140:143], v[216:219], v[72:75]
	s_setprio 0
	s_setprio 1
	v_mfma_f32_16x16x32_bf16 v[116:119], v[158:161], v[184:187], v[116:119]
	v_mfma_f32_16x16x32_bf16 v[112:115], v[166:169], v[184:187], v[112:115]
	v_mfma_f32_16x16x32_bf16 v[100:103], v[158:161], v[192:195], v[100:103]
	v_mfma_f32_16x16x32_bf16 v[96:99], v[166:169], v[192:195], v[96:99]
	v_mfma_f32_16x16x32_bf16 v[84:87], v[158:161], v[200:203], v[84:87]
	v_mfma_f32_16x16x32_bf16 v[80:83], v[166:169], v[200:203], v[80:83]
	v_mfma_f32_16x16x32_bf16 v[68:71], v[158:161], v[208:211], v[68:71]
	v_mfma_f32_16x16x32_bf16 v[64:67], v[166:169], v[208:211], v[64:67]
	v_mfma_f32_16x16x32_bf16 v[116:119], v[162:165], v[188:191], v[116:119]
	v_mfma_f32_16x16x32_bf16 v[112:115], v[180:183], v[188:191], v[112:115]
	v_mfma_f32_16x16x32_bf16 v[100:103], v[162:165], v[196:199], v[100:103]
	v_mfma_f32_16x16x32_bf16 v[96:99], v[180:183], v[196:199], v[96:99]
	v_mfma_f32_16x16x32_bf16 v[84:87], v[162:165], v[204:207], v[84:87]
	v_mfma_f32_16x16x32_bf16 v[80:83], v[180:183], v[204:207], v[80:83]
	v_mfma_f32_16x16x32_bf16 v[68:71], v[162:165], v[216:219], v[68:71]
	v_mfma_f32_16x16x32_bf16 v[64:67], v[180:183], v[216:219], v[64:67]
	s_setprio 0
	s_barrier
	s_add_i32 s24, s76, s56
	v_lshl_add_u64 v[170:171], v[170:171], 0, s[16:17]
	s_mov_b32 m0, s24
	ds_read_b128 v[184:187], v179 offset:49152
	ds_read_b128 v[188:191], v179 offset:50176
	ds_read_b128 v[192:195], v179 offset:51200
	ds_read_b128 v[196:199], v179 offset:52224
	ds_read_b128 v[200:203], v179 offset:53248
	ds_read_b128 v[204:207], v179 offset:54272
	ds_read_b128 v[208:211], v179 offset:55296
	ds_read_b128 v[216:219], v179 offset:56320
	global_load_lds_dwordx4 v[170:171], off
	s_add_i32 m0, s24, 0x2000
	s_add_u32 s24, s28, 0xb0080
	v_lshl_add_u64 v[170:171], v[212:213], 0, s[16:17]
	s_addc_u32 s25, s29, 0
	s_add_i32 s28, s77, s56
	global_load_lds_dwordx4 v[170:171], off
	v_lshl_add_u64 v[170:171], s[24:25], 0, v[146:147]
	s_mov_b32 m0, s28
	s_nop 0
	global_load_lds_dwordx4 v[170:171], off
	v_lshl_add_u64 v[170:171], s[24:25], 0, v[150:151]
	s_add_i32 m0, s28, 0x2000
	s_nop 0
	global_load_lds_dwordx4 v[170:171], off
	v_lshl_add_u64 v[170:171], v[220:221], 0, s[16:17]
	s_mov_b32 m0, s64
	s_nop 0
	global_load_lds_dwordx4 v[170:171], off
	v_lshl_add_u64 v[170:171], v[222:223], 0, s[16:17]
	s_mov_b32 m0, s65
	s_nop 0
	global_load_lds_dwordx4 v[170:171], off
	s_waitcnt vmcnt(8)
	s_waitcnt lgkmcnt(0)
	s_barrier
	s_setprio 1
	s_waitcnt lgkmcnt(0)
	v_mfma_f32_16x16x32_bf16 v[60:63], v[128:131], v[184:187], v[60:63]
	v_mfma_f32_16x16x32_bf16 v[56:59], v[136:139], v[184:187], v[56:59]
	v_mfma_f32_16x16x32_bf16 v[44:47], v[128:131], v[192:195], v[44:47]
	v_mfma_f32_16x16x32_bf16 v[40:43], v[136:139], v[192:195], v[40:43]
	v_mfma_f32_16x16x32_bf16 v[28:31], v[128:131], v[200:203], v[28:31]
	v_mfma_f32_16x16x32_bf16 v[24:27], v[136:139], v[200:203], v[24:27]
	v_mfma_f32_16x16x32_bf16 v[12:15], v[128:131], v[208:211], v[12:15]
	v_mfma_f32_16x16x32_bf16 v[8:11], v[136:139], v[208:211], v[8:11]
	v_mfma_f32_16x16x32_bf16 v[60:63], v[132:135], v[188:191], v[60:63]
	v_mfma_f32_16x16x32_bf16 v[56:59], v[140:143], v[188:191], v[56:59]
	v_mfma_f32_16x16x32_bf16 v[44:47], v[132:135], v[196:199], v[44:47]
	v_mfma_f32_16x16x32_bf16 v[40:43], v[140:143], v[196:199], v[40:43]
	v_mfma_f32_16x16x32_bf16 v[28:31], v[132:135], v[204:207], v[28:31]
	v_mfma_f32_16x16x32_bf16 v[24:27], v[140:143], v[204:207], v[24:27]
	v_mfma_f32_16x16x32_bf16 v[12:15], v[132:135], v[216:219], v[12:15]
	v_mfma_f32_16x16x32_bf16 v[8:11], v[140:143], v[216:219], v[8:11]
	s_setprio 0
	s_setprio 1
	v_mfma_f32_16x16x32_bf16 v[52:55], v[158:161], v[184:187], v[52:55]
	v_mfma_f32_16x16x32_bf16 v[48:51], v[166:169], v[184:187], v[48:51]
	v_mfma_f32_16x16x32_bf16 v[36:39], v[158:161], v[192:195], v[36:39]
	v_mfma_f32_16x16x32_bf16 v[32:35], v[166:169], v[192:195], v[32:35]
	v_mfma_f32_16x16x32_bf16 v[20:23], v[158:161], v[200:203], v[20:23]
	v_mfma_f32_16x16x32_bf16 v[16:19], v[166:169], v[200:203], v[16:19]
	v_mfma_f32_16x16x32_bf16 v[4:7], v[158:161], v[208:211], v[4:7]
	v_mfma_f32_16x16x32_bf16 v[0:3], v[166:169], v[208:211], v[0:3]
	v_mfma_f32_16x16x32_bf16 v[52:55], v[162:165], v[188:191], v[52:55]
	v_mfma_f32_16x16x32_bf16 v[48:51], v[180:183], v[188:191], v[48:51]
	v_mfma_f32_16x16x32_bf16 v[36:39], v[162:165], v[196:199], v[36:39]
	v_mfma_f32_16x16x32_bf16 v[32:35], v[180:183], v[196:199], v[32:35]
	v_mfma_f32_16x16x32_bf16 v[20:23], v[162:165], v[204:207], v[20:23]
	v_mfma_f32_16x16x32_bf16 v[16:19], v[180:183], v[204:207], v[16:19]
	v_mfma_f32_16x16x32_bf16 v[4:7], v[162:165], v[216:219], v[4:7]
	v_mfma_f32_16x16x32_bf16 v[0:3], v[180:183], v[216:219], v[0:3]
	s_setprio 0
	s_barrier
	s_add_i32 s72, s72, 2
	s_add_u32 s12, s12, 0x100
	s_addc_u32 s74, s74, 0
	s_cmp_gt_u32 s72, 41
	s_mov_b64 s[24:25], s[26:27]

.LBB0_706:
	s_ashr_i32 s27, s26, 31
	s_lshl_b64 s[8:9], s[26:27], 19
	s_add_u32 s28, s46, s8
	s_addc_u32 s29, s47, s9
	s_and_b64 s[8:9], s[2:3], exec
	s_cselect_b32 s11, s29, s5
	s_cselect_b32 s27, s28, s4
	s_ashr_i32 s25, s24, 31
	s_lshl_b64 s[8:9], s[24:25], 19
	s_add_u32 s30, s60, s8
	s_addc_u32 s31, s61, s9
	s_and_b64 s[8:9], s[2:3], exec
	s_cselect_b32 s25, s31, s7
	s_cselect_b32 s53, s30, s6
	s_add_u32 s4, s4, 0x40080
	s_addc_u32 s5, s5, 0
	s_add_u32 s54, s6, 0x100
	s_addc_u32 s55, s7, 0
	s_mov_b32 s56, -2
	ds_read_b128 v[48:51], v196
	ds_read_b128 v[52:55], v196 offset:1024
	ds_read_b128 v[56:59], v196 offset:2048
	ds_read_b128 v[60:63], v196 offset:3072
	ds_read_b128 v[162:165], v197
	ds_read_b128 v[166:169], v197 offset:1024
	ds_read_b128 v[170:173], v197 offset:2048
	ds_read_b128 v[174:177], v197 offset:3072
	s_add_u32 s6, s4, 0xfffc0080
	s_addc_u32 s7, s5, -1
	s_cmp_eq_u32 s56, 12
	s_cselect_b32 s9, s11, s7
	s_cselect_b32 s8, s27, s6
	s_cselect_b32 s7, s25, s55
	s_cselect_b32 s6, s53, s54
	v_lshl_add_u64 v[190:191], s[4:5], 0, v[154:155]
	s_add_i32 m0, s63, 0xc000
	ds_read_b128 v[178:181], v198
	ds_read_b128 v[182:185], v198 offset:1024
	ds_read_b128 v[186:189], v198 offset:2048
	ds_read_b128 v[200:203], v198 offset:3072
	ds_read_b128 v[204:207], v198 offset:4096
	ds_read_b128 v[208:211], v198 offset:5120
	ds_read_b128 v[216:219], v198 offset:6144
	ds_read_b128 v[220:223], v198 offset:7168
	global_load_lds_dwordx4 v[190:191], off
	v_lshl_add_u64 v[190:191], s[4:5], 0, v[156:157]
	s_add_i32 m0, s63, 0xe000
	s_nop 0
	global_load_lds_dwordx4 v[190:191], off
	s_waitcnt vmcnt(8)
	s_waitcnt lgkmcnt(0)
	s_barrier
	s_setprio 1
	s_waitcnt lgkmcnt(0)
	v_mfma_f32_16x16x32_bf16 v[140:143], v[48:51], v[178:181], 0
	v_mfma_f32_16x16x32_bf16 v[136:139], v[56:59], v[178:181], 0
	v_mfma_f32_16x16x32_bf16 v[124:127], v[48:51], v[186:189], 0
	v_mfma_f32_16x16x32_bf16 v[120:123], v[56:59], v[186:189], 0
	v_mfma_f32_16x16x32_bf16 v[108:111], v[48:51], v[204:207], 0
	v_mfma_f32_16x16x32_bf16 v[104:107], v[56:59], v[204:207], 0
	v_mfma_f32_16x16x32_bf16 v[92:95], v[48:51], v[216:219], 0
	v_mfma_f32_16x16x32_bf16 v[88:91], v[56:59], v[216:219], 0
	v_mfma_f32_16x16x32_bf16 v[140:143], v[52:55], v[182:185], v[140:143]
	v_mfma_f32_16x16x32_bf16 v[136:139], v[60:63], v[182:185], v[136:139]
	v_mfma_f32_16x16x32_bf16 v[124:127], v[52:55], v[200:203], v[124:127]
	v_mfma_f32_16x16x32_bf16 v[120:123], v[60:63], v[200:203], v[120:123]
	v_mfma_f32_16x16x32_bf16 v[108:111], v[52:55], v[208:211], v[108:111]
	v_mfma_f32_16x16x32_bf16 v[104:107], v[60:63], v[208:211], v[104:107]
	v_mfma_f32_16x16x32_bf16 v[92:95], v[52:55], v[220:223], v[92:95]
	v_mfma_f32_16x16x32_bf16 v[88:91], v[60:63], v[220:223], v[88:91]
	s_setprio 0
	s_setprio 1
	v_mfma_f32_16x16x32_bf16 v[132:135], v[162:165], v[178:181], 0
	v_mfma_f32_16x16x32_bf16 v[128:131], v[170:173], v[178:181], 0
	v_mfma_f32_16x16x32_bf16 v[116:119], v[162:165], v[186:189], 0
	v_mfma_f32_16x16x32_bf16 v[112:115], v[170:173], v[186:189], 0
	v_mfma_f32_16x16x32_bf16 v[100:103], v[162:165], v[204:207], 0
	v_mfma_f32_16x16x32_bf16 v[96:99], v[170:173], v[204:207], 0
	v_mfma_f32_16x16x32_bf16 v[84:87], v[162:165], v[216:219], 0
	v_mfma_f32_16x16x32_bf16 v[80:83], v[170:173], v[216:219], 0
	v_mfma_f32_16x16x32_bf16 v[132:135], v[166:169], v[182:185], v[132:135]
	v_mfma_f32_16x16x32_bf16 v[128:131], v[174:177], v[182:185], v[128:131]
	v_mfma_f32_16x16x32_bf16 v[116:119], v[166:169], v[200:203], v[116:119]
	v_mfma_f32_16x16x32_bf16 v[112:115], v[174:177], v[200:203], v[112:115]
	v_mfma_f32_16x16x32_bf16 v[100:103], v[166:169], v[208:211], v[100:103]
	v_mfma_f32_16x16x32_bf16 v[96:99], v[174:177], v[208:211], v[96:99]
	v_mfma_f32_16x16x32_bf16 v[84:87], v[166:169], v[220:223], v[84:87]
	v_mfma_f32_16x16x32_bf16 v[80:83], v[174:177], v[220:223], v[80:83]
	s_setprio 0
	s_barrier
	s_add_i32 s57, s87, s62
	v_lshl_add_u64 v[190:191], s[6:7], 0, v[144:145]
	s_mov_b32 m0, s57
	ds_read_b128 v[178:181], v198 offset:16384
	ds_read_b128 v[182:185], v198 offset:17408
	ds_read_b128 v[186:189], v198 offset:18432
	ds_read_b128 v[200:203], v198 offset:19456
	ds_read_b128 v[204:207], v198 offset:20480
	ds_read_b128 v[208:211], v198 offset:21504
	ds_read_b128 v[216:219], v198 offset:22528
	ds_read_b128 v[220:223], v198 offset:23552
	global_load_lds_dwordx4 v[190:191], off
	s_add_i32 m0, s57, 0x2000
	s_add_u32 s58, s6, 0x40000
	v_lshl_add_u64 v[212:213], s[6:7], 0, v[146:147]
	s_addc_u32 s59, s7, 0
	s_add_i32 s57, s88, s62
	global_load_lds_dwordx4 v[212:213], off
	v_lshl_add_u64 v[224:225], s[58:59], 0, v[144:145]
	s_mov_b32 m0, s57
	v_lshl_add_u64 v[226:227], s[8:9], 0, v[146:147]
	global_load_lds_dwordx4 v[224:225], off
	v_lshl_add_u64 v[224:225], s[58:59], 0, v[146:147]
	s_add_i32 m0, s57, 0x2000
	s_nop 0
	global_load_lds_dwordx4 v[224:225], off
	v_lshl_add_u64 v[224:225], s[8:9], 0, v[144:145]
	s_mov_b32 m0, s63
	s_nop 0
	global_load_lds_dwordx4 v[224:225], off
	s_mov_b32 m0, s64
	s_nop 0
	global_load_lds_dwordx4 v[226:227], off
	s_waitcnt vmcnt(8)
	s_waitcnt lgkmcnt(0)
	s_barrier
	s_setprio 1
	s_waitcnt lgkmcnt(0)
	v_mfma_f32_16x16x32_bf16 v[76:79], v[48:51], v[178:181], 0
	v_mfma_f32_16x16x32_bf16 v[72:75], v[56:59], v[178:181], 0
	v_mfma_f32_16x16x32_bf16 v[44:47], v[48:51], v[186:189], 0
	v_mfma_f32_16x16x32_bf16 v[40:43], v[56:59], v[186:189], 0
	v_mfma_f32_16x16x32_bf16 v[28:31], v[48:51], v[204:207], 0
	v_mfma_f32_16x16x32_bf16 v[24:27], v[56:59], v[204:207], 0
	v_mfma_f32_16x16x32_bf16 v[12:15], v[48:51], v[216:219], 0
	v_mfma_f32_16x16x32_bf16 v[8:11], v[56:59], v[216:219], 0
	v_mfma_f32_16x16x32_bf16 v[76:79], v[52:55], v[182:185], v[76:79]
	v_mfma_f32_16x16x32_bf16 v[72:75], v[60:63], v[182:185], v[72:75]
	v_mfma_f32_16x16x32_bf16 v[44:47], v[52:55], v[200:203], v[44:47]
	v_mfma_f32_16x16x32_bf16 v[40:43], v[60:63], v[200:203], v[40:43]
	v_mfma_f32_16x16x32_bf16 v[28:31], v[52:55], v[208:211], v[28:31]
	v_mfma_f32_16x16x32_bf16 v[24:27], v[60:63], v[208:211], v[24:27]
	v_mfma_f32_16x16x32_bf16 v[12:15], v[52:55], v[220:223], v[12:15]
	v_mfma_f32_16x16x32_bf16 v[8:11], v[60:63], v[220:223], v[8:11]
	s_setprio 0
	s_setprio 1
	v_mfma_f32_16x16x32_bf16 v[36:39], v[162:165], v[186:189], 0
	v_mfma_f32_16x16x32_bf16 v[32:35], v[170:173], v[186:189], 0
	v_mfma_f32_16x16x32_bf16 v[20:23], v[162:165], v[204:207], 0
	v_mfma_f32_16x16x32_bf16 v[16:19], v[170:173], v[204:207], 0
	v_mfma_f32_16x16x32_bf16 v[4:7], v[162:165], v[216:219], 0
	v_mfma_f32_16x16x32_bf16 v[0:3], v[170:173], v[216:219], 0
	v_mfma_f32_16x16x32_bf16 v[48:51], v[162:165], v[178:181], 0
	v_mfma_f32_16x16x32_bf16 v[52:55], v[170:173], v[178:181], 0
	v_mfma_f32_16x16x32_bf16 v[36:39], v[166:169], v[200:203], v[36:39]
	v_mfma_f32_16x16x32_bf16 v[32:35], v[174:177], v[200:203], v[32:35]
	v_mfma_f32_16x16x32_bf16 v[20:23], v[166:169], v[208:211], v[20:23]
	v_mfma_f32_16x16x32_bf16 v[16:19], v[174:177], v[208:211], v[16:19]
	v_mfma_f32_16x16x32_bf16 v[4:7], v[166:169], v[220:223], v[4:7]
	v_mfma_f32_16x16x32_bf16 v[0:3], v[174:177], v[220:223], v[0:3]
	v_mfma_f32_16x16x32_bf16 v[48:51], v[166:169], v[182:185], v[48:51]
	v_mfma_f32_16x16x32_bf16 v[52:55], v[174:177], v[182:185], v[52:55]
	s_setprio 0
	s_barrier
	s_add_i32 s57, 0, 0x18000
	s_add_i32 s58, 0, 0x1c000
	v_add_u32_e32 v68, s57, v193
	v_add_u32_e32 v174, s58, v193
	ds_read_b128 v[56:59], v68
	ds_read_b128 v[60:63], v68 offset:1024
	ds_read_b128 v[64:67], v68 offset:2048
	ds_read_b128 v[68:71], v68 offset:3072
	ds_read_b128 v[162:165], v174
	ds_read_b128 v[166:169], v174 offset:1024
	ds_read_b128 v[170:173], v174 offset:2048
	ds_read_b128 v[174:177], v174 offset:3072
	s_add_u32 s8, s8, 0x40000
	s_addc_u32 s9, s9, 0
	s_mov_b32 m0, s65
	v_lshl_add_u64 v[228:229], s[8:9], 0, v[144:145]
	ds_read_b128 v[178:181], v198 offset:32768
	ds_read_b128 v[182:185], v198 offset:33792
	ds_read_b128 v[186:189], v198 offset:34816
	ds_read_b128 v[200:203], v198 offset:35840
	ds_read_b128 v[204:207], v198 offset:36864
	ds_read_b128 v[208:211], v198 offset:37888
	ds_read_b128 v[216:219], v198 offset:38912
	ds_read_b128 v[220:223], v198 offset:39936
	global_load_lds_dwordx4 v[228:229], off
	v_lshl_add_u64 v[228:229], s[8:9], 0, v[146:147]
	s_mov_b32 m0, s66
	s_nop 0
	global_load_lds_dwordx4 v[228:229], off
	s_waitcnt vmcnt(8)
	s_waitcnt lgkmcnt(0)
	s_barrier
	s_setprio 1
	s_waitcnt lgkmcnt(0)
	v_mfma_f32_16x16x32_bf16 v[140:143], v[56:59], v[178:181], v[140:143]
	v_mfma_f32_16x16x32_bf16 v[136:139], v[64:67], v[178:181], v[136:139]
	v_mfma_f32_16x16x32_bf16 v[124:127], v[56:59], v[186:189], v[124:127]
	v_mfma_f32_16x16x32_bf16 v[120:123], v[64:67], v[186:189], v[120:123]
	v_mfma_f32_16x16x32_bf16 v[108:111], v[56:59], v[204:207], v[108:111]
	v_mfma_f32_16x16x32_bf16 v[104:107], v[64:67], v[204:207], v[104:107]
	v_mfma_f32_16x16x32_bf16 v[92:95], v[56:59], v[216:219], v[92:95]
	v_mfma_f32_16x16x32_bf16 v[88:91], v[64:67], v[216:219], v[88:91]
	v_mfma_f32_16x16x32_bf16 v[140:143], v[60:63], v[182:185], v[140:143]
	v_mfma_f32_16x16x32_bf16 v[136:139], v[68:71], v[182:185], v[136:139]
	v_mfma_f32_16x16x32_bf16 v[124:127], v[60:63], v[200:203], v[124:127]
	v_mfma_f32_16x16x32_bf16 v[120:123], v[68:71], v[200:203], v[120:123]
	v_mfma_f32_16x16x32_bf16 v[108:111], v[60:63], v[208:211], v[108:111]
	v_mfma_f32_16x16x32_bf16 v[104:107], v[68:71], v[208:211], v[104:107]
	v_mfma_f32_16x16x32_bf16 v[92:95], v[60:63], v[220:223], v[92:95]
	v_mfma_f32_16x16x32_bf16 v[88:91], v[68:71], v[220:223], v[88:91]
	s_setprio 0
	s_setprio 1
	v_mfma_f32_16x16x32_bf16 v[132:135], v[162:165], v[178:181], v[132:135]
	v_mfma_f32_16x16x32_bf16 v[128:131], v[170:173], v[178:181], v[128:131]
	v_mfma_f32_16x16x32_bf16 v[116:119], v[162:165], v[186:189], v[116:119]
	v_mfma_f32_16x16x32_bf16 v[112:115], v[170:173], v[186:189], v[112:115]
	v_mfma_f32_16x16x32_bf16 v[100:103], v[162:165], v[204:207], v[100:103]
	v_mfma_f32_16x16x32_bf16 v[96:99], v[170:173], v[204:207], v[96:99]
	v_mfma_f32_16x16x32_bf16 v[84:87], v[162:165], v[216:219], v[84:87]
	v_mfma_f32_16x16x32_bf16 v[80:83], v[170:173], v[216:219], v[80:83]
	v_mfma_f32_16x16x32_bf16 v[132:135], v[166:169], v[182:185], v[132:135]
	v_mfma_f32_16x16x32_bf16 v[128:131], v[174:177], v[182:185], v[128:131]
	v_mfma_f32_16x16x32_bf16 v[116:119], v[166:169], v[200:203], v[116:119]
	v_mfma_f32_16x16x32_bf16 v[112:115], v[174:177], v[200:203], v[112:115]
	v_mfma_f32_16x16x32_bf16 v[100:103], v[166:169], v[208:211], v[100:103]
	v_mfma_f32_16x16x32_bf16 v[96:99], v[174:177], v[208:211], v[96:99]
	v_mfma_f32_16x16x32_bf16 v[84:87], v[166:169], v[220:223], v[84:87]
	v_mfma_f32_16x16x32_bf16 v[80:83], v[174:177], v[220:223], v[80:83]
	s_setprio 0
	s_barrier
	s_add_i32 s8, s57, s62
	v_lshl_add_u64 v[190:191], v[190:191], 0, s[20:21]
	s_mov_b32 m0, s8
	ds_read_b128 v[178:181], v198 offset:49152
	ds_read_b128 v[182:185], v198 offset:50176
	ds_read_b128 v[186:189], v198 offset:51200
	ds_read_b128 v[200:203], v198 offset:52224
	ds_read_b128 v[204:207], v198 offset:53248
	ds_read_b128 v[208:211], v198 offset:54272
	ds_read_b128 v[216:219], v198 offset:55296
	ds_read_b128 v[220:223], v198 offset:56320
	global_load_lds_dwordx4 v[190:191], off
	s_add_i32 m0, s8, 0x2000
	s_add_u32 s6, s6, 0x40080
	v_lshl_add_u64 v[190:191], v[212:213], 0, s[20:21]
	s_addc_u32 s7, s7, 0
	s_add_i32 s8, s58, s62
	global_load_lds_dwordx4 v[190:191], off
	v_lshl_add_u64 v[190:191], s[6:7], 0, v[144:145]
	s_mov_b32 m0, s8
	s_nop 0
	global_load_lds_dwordx4 v[190:191], off
	v_lshl_add_u64 v[190:191], s[6:7], 0, v[146:147]
	s_add_i32 m0, s8, 0x2000
	s_nop 0
	global_load_lds_dwordx4 v[190:191], off
	v_lshl_add_u64 v[190:191], v[224:225], 0, s[20:21]
	s_mov_b32 m0, s81
	s_nop 0
	global_load_lds_dwordx4 v[190:191], off
	v_lshl_add_u64 v[190:191], v[226:227], 0, s[20:21]
	s_mov_b32 m0, s82
	s_nop 0
	global_load_lds_dwordx4 v[190:191], off
	s_waitcnt vmcnt(8)
	s_waitcnt lgkmcnt(0)
	s_barrier
	s_setprio 1
	s_waitcnt lgkmcnt(0)
	v_mfma_f32_16x16x32_bf16 v[76:79], v[56:59], v[178:181], v[76:79]
	v_mfma_f32_16x16x32_bf16 v[72:75], v[64:67], v[178:181], v[72:75]
	v_mfma_f32_16x16x32_bf16 v[44:47], v[56:59], v[186:189], v[44:47]
	v_mfma_f32_16x16x32_bf16 v[40:43], v[64:67], v[186:189], v[40:43]
	v_mfma_f32_16x16x32_bf16 v[28:31], v[56:59], v[204:207], v[28:31]
	v_mfma_f32_16x16x32_bf16 v[24:27], v[64:67], v[204:207], v[24:27]
	v_mfma_f32_16x16x32_bf16 v[12:15], v[56:59], v[216:219], v[12:15]
	v_mfma_f32_16x16x32_bf16 v[8:11], v[64:67], v[216:219], v[8:11]
	v_mfma_f32_16x16x32_bf16 v[76:79], v[60:63], v[182:185], v[76:79]
	v_mfma_f32_16x16x32_bf16 v[72:75], v[68:71], v[182:185], v[72:75]
	v_mfma_f32_16x16x32_bf16 v[44:47], v[60:63], v[200:203], v[44:47]
	v_mfma_f32_16x16x32_bf16 v[40:43], v[68:71], v[200:203], v[40:43]
	v_mfma_f32_16x16x32_bf16 v[28:31], v[60:63], v[208:211], v[28:31]
	v_mfma_f32_16x16x32_bf16 v[24:27], v[68:71], v[208:211], v[24:27]
	v_mfma_f32_16x16x32_bf16 v[12:15], v[60:63], v[220:223], v[12:15]
	v_mfma_f32_16x16x32_bf16 v[8:11], v[68:71], v[220:223], v[8:11]
	s_setprio 0
	s_setprio 1
	v_mfma_f32_16x16x32_bf16 v[48:51], v[162:165], v[178:181], v[48:51]
	v_mfma_f32_16x16x32_bf16 v[68:71], v[166:169], v[182:185], v[48:51]
	v_mfma_f32_16x16x32_bf16 v[48:51], v[170:173], v[178:181], v[52:55]
	v_mfma_f32_16x16x32_bf16 v[36:39], v[162:165], v[186:189], v[36:39]
	v_mfma_f32_16x16x32_bf16 v[32:35], v[170:173], v[186:189], v[32:35]
	v_mfma_f32_16x16x32_bf16 v[20:23], v[162:165], v[204:207], v[20:23]
	v_mfma_f32_16x16x32_bf16 v[16:19], v[170:173], v[204:207], v[16:19]
	v_mfma_f32_16x16x32_bf16 v[4:7], v[162:165], v[216:219], v[4:7]
	v_mfma_f32_16x16x32_bf16 v[0:3], v[170:173], v[216:219], v[0:3]
	v_mfma_f32_16x16x32_bf16 v[64:67], v[174:177], v[182:185], v[48:51]
	v_mfma_f32_16x16x32_bf16 v[36:39], v[166:169], v[200:203], v[36:39]
	v_mfma_f32_16x16x32_bf16 v[32:35], v[174:177], v[200:203], v[32:35]
	v_mfma_f32_16x16x32_bf16 v[20:23], v[166:169], v[208:211], v[20:23]
	v_mfma_f32_16x16x32_bf16 v[16:19], v[174:177], v[208:211], v[16:19]
	v_mfma_f32_16x16x32_bf16 v[4:7], v[166:169], v[220:223], v[4:7]
	v_mfma_f32_16x16x32_bf16 v[0:3], v[174:177], v[220:223], v[0:3]
	s_setprio 0
	s_barrier
	s_add_i32 s56, s56, 2
	s_add_u32 s4, s4, 0x100
	s_addc_u32 s5, s5, 0
	s_add_u32 s54, s54, 0x100
	s_addc_u32 s55, s55, 0
	s_cmp_gt_u32 s56, 13

.LBB0_1159:
	s_ashr_i32 s23, s22, 31
	s_lshl_b64 s[24:25], s[22:23], 19
	s_add_u32 s24, s42, s24
	s_addc_u32 s25, s43, s25
	s_and_b64 s[26:27], s[4:5], exec
	s_cselect_b32 s23, s25, s31
	s_cselect_b32 s29, s24, s30
	s_ashr_i32 s21, s20, 31
	s_lshl_b64 s[26:27], s[20:21], 19
	s_add_u32 s26, s54, s26
	s_addc_u32 s27, s55, s27
	s_and_b64 s[52:53], s[4:5], exec
	s_cselect_b32 s21, s27, s45
	s_cselect_b32 s69, s26, s44
	s_add_u32 s30, s30, 0x40080
	s_addc_u32 s31, s31, 0
	s_add_u32 s70, s44, 0x100
	s_addc_u32 s71, s45, 0
	s_mov_b32 s72, -2
	s_waitcnt lgkmcnt(0)
	ds_read_b128 v[128:131], v179
	ds_read_b128 v[132:135], v179 offset:1024
	ds_read_b128 v[136:139], v179 offset:2048
	ds_read_b128 v[140:143], v179 offset:3072
	ds_read_b128 v[160:163], v180
	ds_read_b128 v[164:167], v180 offset:1024
	ds_read_b128 v[168:171], v180 offset:2048
	ds_read_b128 v[182:185], v180 offset:3072
	s_add_u32 s44, s30, 0xfffc0080
	s_addc_u32 s45, s31, -1
	s_cmp_eq_u32 s72, 12
	s_cselect_b32 s53, s23, s45
	s_cselect_b32 s52, s29, s44
	s_cselect_b32 s45, s21, s71
	s_cselect_b32 s44, s69, s70
	v_lshl_add_u64 v[172:173], s[30:31], 0, v[152:153]
	s_add_i32 m0, s57, 0xc000
	ds_read_b128 v[186:189], v181
	ds_read_b128 v[190:193], v181 offset:1024
	ds_read_b128 v[194:197], v181 offset:2048
	ds_read_b128 v[198:201], v181 offset:3072
	ds_read_b128 v[202:205], v181 offset:4096
	ds_read_b128 v[206:209], v181 offset:5120
	ds_read_b128 v[210:213], v181 offset:6144
	ds_read_b128 v[216:219], v181 offset:7168
	global_load_lds_dwordx4 v[172:173], off
	v_lshl_add_u64 v[172:173], s[30:31], 0, v[154:155]
	s_add_i32 m0, s57, 0xe000
	s_nop 0
	global_load_lds_dwordx4 v[172:173], off
	s_waitcnt vmcnt(8)
	s_waitcnt lgkmcnt(0)
	s_barrier
	s_setprio 1
	s_waitcnt lgkmcnt(0)
	v_mfma_f32_16x16x32_bf16 v[124:127], v[128:131], v[186:189], 0
	v_mfma_f32_16x16x32_bf16 v[120:123], v[136:139], v[186:189], 0
	v_mfma_f32_16x16x32_bf16 v[108:111], v[128:131], v[194:197], 0
	v_mfma_f32_16x16x32_bf16 v[104:107], v[136:139], v[194:197], 0
	v_mfma_f32_16x16x32_bf16 v[92:95], v[128:131], v[202:205], 0
	v_mfma_f32_16x16x32_bf16 v[88:91], v[136:139], v[202:205], 0
	v_mfma_f32_16x16x32_bf16 v[76:79], v[128:131], v[210:213], 0
	v_mfma_f32_16x16x32_bf16 v[72:75], v[136:139], v[210:213], 0
	v_mfma_f32_16x16x32_bf16 v[124:127], v[132:135], v[190:193], v[124:127]
	v_mfma_f32_16x16x32_bf16 v[120:123], v[140:143], v[190:193], v[120:123]
	v_mfma_f32_16x16x32_bf16 v[108:111], v[132:135], v[198:201], v[108:111]
	v_mfma_f32_16x16x32_bf16 v[104:107], v[140:143], v[198:201], v[104:107]
	v_mfma_f32_16x16x32_bf16 v[92:95], v[132:135], v[206:209], v[92:95]
	v_mfma_f32_16x16x32_bf16 v[88:91], v[140:143], v[206:209], v[88:91]
	v_mfma_f32_16x16x32_bf16 v[76:79], v[132:135], v[216:219], v[76:79]
	v_mfma_f32_16x16x32_bf16 v[72:75], v[140:143], v[216:219], v[72:75]
	s_setprio 0
	s_setprio 1
	v_mfma_f32_16x16x32_bf16 v[116:119], v[160:163], v[186:189], 0
	v_mfma_f32_16x16x32_bf16 v[112:115], v[168:171], v[186:189], 0
	v_mfma_f32_16x16x32_bf16 v[100:103], v[160:163], v[194:197], 0
	v_mfma_f32_16x16x32_bf16 v[96:99], v[168:171], v[194:197], 0
	v_mfma_f32_16x16x32_bf16 v[84:87], v[160:163], v[202:205], 0
	v_mfma_f32_16x16x32_bf16 v[80:83], v[168:171], v[202:205], 0
	v_mfma_f32_16x16x32_bf16 v[68:71], v[160:163], v[210:213], 0
	v_mfma_f32_16x16x32_bf16 v[64:67], v[168:171], v[210:213], 0
	v_mfma_f32_16x16x32_bf16 v[116:119], v[164:167], v[190:193], v[116:119]
	v_mfma_f32_16x16x32_bf16 v[112:115], v[182:185], v[190:193], v[112:115]
	v_mfma_f32_16x16x32_bf16 v[100:103], v[164:167], v[198:201], v[100:103]
	v_mfma_f32_16x16x32_bf16 v[96:99], v[182:185], v[198:201], v[96:99]
	v_mfma_f32_16x16x32_bf16 v[84:87], v[164:167], v[206:209], v[84:87]
	v_mfma_f32_16x16x32_bf16 v[80:83], v[182:185], v[206:209], v[80:83]
	v_mfma_f32_16x16x32_bf16 v[68:71], v[164:167], v[216:219], v[68:71]
	v_mfma_f32_16x16x32_bf16 v[64:67], v[182:185], v[216:219], v[64:67]
	s_setprio 0
	s_barrier
	s_add_i32 s73, s66, s56
	v_lshl_add_u64 v[172:173], s[44:45], 0, v[146:147]
	s_mov_b32 m0, s73
	ds_read_b128 v[186:189], v181 offset:16384
	ds_read_b128 v[190:193], v181 offset:17408
	ds_read_b128 v[194:197], v181 offset:18432
	ds_read_b128 v[198:201], v181 offset:19456
	ds_read_b128 v[202:205], v181 offset:20480
	ds_read_b128 v[206:209], v181 offset:21504
	ds_read_b128 v[210:213], v181 offset:22528
	ds_read_b128 v[216:219], v181 offset:23552
	global_load_lds_dwordx4 v[172:173], off
	s_add_i32 m0, s73, 0x2000
	s_add_u32 s76, s44, 0x40000
	v_lshl_add_u64 v[220:221], s[44:45], 0, v[150:151]
	s_addc_u32 s77, s45, 0
	s_add_i32 s73, s67, s56
	global_load_lds_dwordx4 v[220:221], off
	v_lshl_add_u64 v[222:223], s[76:77], 0, v[146:147]
	s_mov_b32 m0, s73
	v_lshl_add_u64 v[224:225], s[52:53], 0, v[148:149]
	global_load_lds_dwordx4 v[222:223], off
	v_lshl_add_u64 v[222:223], s[76:77], 0, v[150:151]
	s_add_i32 m0, s73, 0x2000
	s_nop 0
	global_load_lds_dwordx4 v[222:223], off
	v_lshl_add_u64 v[222:223], s[52:53], 0, v[144:145]
	s_mov_b32 m0, s57
	s_nop 0
	global_load_lds_dwordx4 v[222:223], off
	s_mov_b32 m0, s58
	s_nop 0
	global_load_lds_dwordx4 v[224:225], off
	s_waitcnt vmcnt(8)
	s_waitcnt lgkmcnt(0)
	s_barrier
	s_setprio 1
	s_waitcnt lgkmcnt(0)
	v_mfma_f32_16x16x32_bf16 v[60:63], v[128:131], v[186:189], 0
	v_mfma_f32_16x16x32_bf16 v[56:59], v[136:139], v[186:189], 0
	v_mfma_f32_16x16x32_bf16 v[44:47], v[128:131], v[194:197], 0
	v_mfma_f32_16x16x32_bf16 v[40:43], v[136:139], v[194:197], 0
	v_mfma_f32_16x16x32_bf16 v[28:31], v[128:131], v[202:205], 0
	v_mfma_f32_16x16x32_bf16 v[24:27], v[136:139], v[202:205], 0
	v_mfma_f32_16x16x32_bf16 v[12:15], v[128:131], v[210:213], 0
	v_mfma_f32_16x16x32_bf16 v[8:11], v[136:139], v[210:213], 0
	v_mfma_f32_16x16x32_bf16 v[60:63], v[132:135], v[190:193], v[60:63]
	v_mfma_f32_16x16x32_bf16 v[56:59], v[140:143], v[190:193], v[56:59]
	v_mfma_f32_16x16x32_bf16 v[44:47], v[132:135], v[198:201], v[44:47]
	v_mfma_f32_16x16x32_bf16 v[40:43], v[140:143], v[198:201], v[40:43]
	v_mfma_f32_16x16x32_bf16 v[28:31], v[132:135], v[206:209], v[28:31]
	v_mfma_f32_16x16x32_bf16 v[24:27], v[140:143], v[206:209], v[24:27]
	v_mfma_f32_16x16x32_bf16 v[12:15], v[132:135], v[216:219], v[12:15]
	v_mfma_f32_16x16x32_bf16 v[8:11], v[140:143], v[216:219], v[8:11]
	s_setprio 0
	s_setprio 1
	v_mfma_f32_16x16x32_bf16 v[52:55], v[160:163], v[186:189], 0
	v_mfma_f32_16x16x32_bf16 v[48:51], v[168:171], v[186:189], 0
	v_mfma_f32_16x16x32_bf16 v[36:39], v[160:163], v[194:197], 0
	v_mfma_f32_16x16x32_bf16 v[32:35], v[168:171], v[194:197], 0
	v_mfma_f32_16x16x32_bf16 v[20:23], v[160:163], v[202:205], 0
	v_mfma_f32_16x16x32_bf16 v[16:19], v[168:171], v[202:205], 0
	v_mfma_f32_16x16x32_bf16 v[4:7], v[160:163], v[210:213], 0
	v_mfma_f32_16x16x32_bf16 v[0:3], v[168:171], v[210:213], 0
	v_mfma_f32_16x16x32_bf16 v[52:55], v[164:167], v[190:193], v[52:55]
	v_mfma_f32_16x16x32_bf16 v[48:51], v[182:185], v[190:193], v[48:51]
	v_mfma_f32_16x16x32_bf16 v[36:39], v[164:167], v[198:201], v[36:39]
	v_mfma_f32_16x16x32_bf16 v[32:35], v[182:185], v[198:201], v[32:35]
	v_mfma_f32_16x16x32_bf16 v[20:23], v[164:167], v[206:209], v[20:23]
	v_mfma_f32_16x16x32_bf16 v[16:19], v[182:185], v[206:209], v[16:19]
	v_mfma_f32_16x16x32_bf16 v[4:7], v[164:167], v[216:219], v[4:7]
	v_mfma_f32_16x16x32_bf16 v[0:3], v[182:185], v[216:219], v[0:3]
	s_setprio 0
	s_barrier
	s_add_i32 s73, 0, 0x18000
	s_add_i32 s74, 0, 0x1c000
	v_add_u32_e32 v140, s73, v177
	v_add_u32_e32 v182, s74, v177
	ds_read_b128 v[128:131], v140
	ds_read_b128 v[132:135], v140 offset:1024
	ds_read_b128 v[136:139], v140 offset:2048
	ds_read_b128 v[140:143], v140 offset:3072
	ds_read_b128 v[160:163], v182
	ds_read_b128 v[164:167], v182 offset:1024
	ds_read_b128 v[168:171], v182 offset:2048
	ds_read_b128 v[182:185], v182 offset:3072
	s_add_u32 s52, s52, 0x40000
	s_addc_u32 s53, s53, 0
	s_mov_b32 m0, s59
	v_lshl_add_u64 v[226:227], s[52:53], 0, v[144:145]
	ds_read_b128 v[186:189], v181 offset:32768
	ds_read_b128 v[190:193], v181 offset:33792
	ds_read_b128 v[194:197], v181 offset:34816
	ds_read_b128 v[198:201], v181 offset:35840
	ds_read_b128 v[202:205], v181 offset:36864
	ds_read_b128 v[206:209], v181 offset:37888
	ds_read_b128 v[210:213], v181 offset:38912
	ds_read_b128 v[216:219], v181 offset:39936
	global_load_lds_dwordx4 v[226:227], off
	v_lshl_add_u64 v[226:227], s[52:53], 0, v[148:149]
	s_mov_b32 m0, s60
	s_nop 0
	global_load_lds_dwordx4 v[226:227], off
	s_waitcnt vmcnt(8)
	s_waitcnt lgkmcnt(0)
	s_barrier
	s_setprio 1
	s_waitcnt lgkmcnt(0)
	v_mfma_f32_16x16x32_bf16 v[124:127], v[128:131], v[186:189], v[124:127]
	v_mfma_f32_16x16x32_bf16 v[120:123], v[136:139], v[186:189], v[120:123]
	v_mfma_f32_16x16x32_bf16 v[108:111], v[128:131], v[194:197], v[108:111]
	v_mfma_f32_16x16x32_bf16 v[104:107], v[136:139], v[194:197], v[104:107]
	v_mfma_f32_16x16x32_bf16 v[92:95], v[128:131], v[202:205], v[92:95]
	v_mfma_f32_16x16x32_bf16 v[88:91], v[136:139], v[202:205], v[88:91]
	v_mfma_f32_16x16x32_bf16 v[76:79], v[128:131], v[210:213], v[76:79]
	v_mfma_f32_16x16x32_bf16 v[72:75], v[136:139], v[210:213], v[72:75]
	v_mfma_f32_16x16x32_bf16 v[124:127], v[132:135], v[190:193], v[124:127]
	v_mfma_f32_16x16x32_bf16 v[120:123], v[140:143], v[190:193], v[120:123]
	v_mfma_f32_16x16x32_bf16 v[108:111], v[132:135], v[198:201], v[108:111]
	v_mfma_f32_16x16x32_bf16 v[104:107], v[140:143], v[198:201], v[104:107]
	v_mfma_f32_16x16x32_bf16 v[92:95], v[132:135], v[206:209], v[92:95]
	v_mfma_f32_16x16x32_bf16 v[88:91], v[140:143], v[206:209], v[88:91]
	v_mfma_f32_16x16x32_bf16 v[76:79], v[132:135], v[216:219], v[76:79]
	v_mfma_f32_16x16x32_bf16 v[72:75], v[140:143], v[216:219], v[72:75]
	s_setprio 0
	s_setprio 1
	v_mfma_f32_16x16x32_bf16 v[116:119], v[160:163], v[186:189], v[116:119]
	v_mfma_f32_16x16x32_bf16 v[112:115], v[168:171], v[186:189], v[112:115]
	v_mfma_f32_16x16x32_bf16 v[100:103], v[160:163], v[194:197], v[100:103]
	v_mfma_f32_16x16x32_bf16 v[96:99], v[168:171], v[194:197], v[96:99]
	v_mfma_f32_16x16x32_bf16 v[84:87], v[160:163], v[202:205], v[84:87]
	v_mfma_f32_16x16x32_bf16 v[80:83], v[168:171], v[202:205], v[80:83]
	v_mfma_f32_16x16x32_bf16 v[68:71], v[160:163], v[210:213], v[68:71]
	v_mfma_f32_16x16x32_bf16 v[64:67], v[168:171], v[210:213], v[64:67]
	v_mfma_f32_16x16x32_bf16 v[116:119], v[164:167], v[190:193], v[116:119]
	v_mfma_f32_16x16x32_bf16 v[112:115], v[182:185], v[190:193], v[112:115]
	v_mfma_f32_16x16x32_bf16 v[100:103], v[164:167], v[198:201], v[100:103]
	v_mfma_f32_16x16x32_bf16 v[96:99], v[182:185], v[198:201], v[96:99]
	v_mfma_f32_16x16x32_bf16 v[84:87], v[164:167], v[206:209], v[84:87]
	v_mfma_f32_16x16x32_bf16 v[80:83], v[182:185], v[206:209], v[80:83]
	v_mfma_f32_16x16x32_bf16 v[68:71], v[164:167], v[216:219], v[68:71]
	v_mfma_f32_16x16x32_bf16 v[64:67], v[182:185], v[216:219], v[64:67]
	s_setprio 0
	s_barrier
	s_add_i32 s52, s73, s56
	v_lshl_add_u64 v[172:173], v[172:173], 0, s[14:15]
	s_mov_b32 m0, s52
	ds_read_b128 v[186:189], v181 offset:49152
	ds_read_b128 v[190:193], v181 offset:50176
	ds_read_b128 v[194:197], v181 offset:51200
	ds_read_b128 v[198:201], v181 offset:52224
	ds_read_b128 v[202:205], v181 offset:53248
	ds_read_b128 v[206:209], v181 offset:54272
	ds_read_b128 v[210:213], v181 offset:55296
	ds_read_b128 v[216:219], v181 offset:56320
	global_load_lds_dwordx4 v[172:173], off
	s_add_i32 m0, s52, 0x2000
	s_add_u32 s44, s44, 0x40080
	v_lshl_add_u64 v[172:173], v[220:221], 0, s[14:15]
	s_addc_u32 s45, s45, 0
	s_add_i32 s52, s74, s56
	global_load_lds_dwordx4 v[172:173], off
	v_lshl_add_u64 v[172:173], s[44:45], 0, v[146:147]
	s_mov_b32 m0, s52
	s_nop 0
	global_load_lds_dwordx4 v[172:173], off
	v_lshl_add_u64 v[172:173], s[44:45], 0, v[150:151]
	s_add_i32 m0, s52, 0x2000
	s_nop 0
	global_load_lds_dwordx4 v[172:173], off
	v_lshl_add_u64 v[172:173], v[222:223], 0, s[14:15]
	s_mov_b32 m0, s64
	s_nop 0
	global_load_lds_dwordx4 v[172:173], off
	v_lshl_add_u64 v[172:173], v[224:225], 0, s[14:15]
	s_mov_b32 m0, s65
	s_nop 0
	global_load_lds_dwordx4 v[172:173], off
	s_waitcnt vmcnt(8)
	s_waitcnt lgkmcnt(0)
	s_barrier
	s_setprio 1
	s_waitcnt lgkmcnt(0)
	v_mfma_f32_16x16x32_bf16 v[60:63], v[128:131], v[186:189], v[60:63]
	v_mfma_f32_16x16x32_bf16 v[56:59], v[136:139], v[186:189], v[56:59]
	v_mfma_f32_16x16x32_bf16 v[44:47], v[128:131], v[194:197], v[44:47]
	v_mfma_f32_16x16x32_bf16 v[40:43], v[136:139], v[194:197], v[40:43]
	v_mfma_f32_16x16x32_bf16 v[28:31], v[128:131], v[202:205], v[28:31]
	v_mfma_f32_16x16x32_bf16 v[24:27], v[136:139], v[202:205], v[24:27]
	v_mfma_f32_16x16x32_bf16 v[12:15], v[128:131], v[210:213], v[12:15]
	v_mfma_f32_16x16x32_bf16 v[8:11], v[136:139], v[210:213], v[8:11]
	v_mfma_f32_16x16x32_bf16 v[60:63], v[132:135], v[190:193], v[60:63]
	v_mfma_f32_16x16x32_bf16 v[56:59], v[140:143], v[190:193], v[56:59]
	v_mfma_f32_16x16x32_bf16 v[44:47], v[132:135], v[198:201], v[44:47]
	v_mfma_f32_16x16x32_bf16 v[40:43], v[140:143], v[198:201], v[40:43]
	v_mfma_f32_16x16x32_bf16 v[28:31], v[132:135], v[206:209], v[28:31]
	v_mfma_f32_16x16x32_bf16 v[24:27], v[140:143], v[206:209], v[24:27]
	v_mfma_f32_16x16x32_bf16 v[12:15], v[132:135], v[216:219], v[12:15]
	v_mfma_f32_16x16x32_bf16 v[8:11], v[140:143], v[216:219], v[8:11]
	s_setprio 0
	s_setprio 1
	v_mfma_f32_16x16x32_bf16 v[52:55], v[160:163], v[186:189], v[52:55]
	v_mfma_f32_16x16x32_bf16 v[48:51], v[168:171], v[186:189], v[48:51]
	v_mfma_f32_16x16x32_bf16 v[36:39], v[160:163], v[194:197], v[36:39]
	v_mfma_f32_16x16x32_bf16 v[32:35], v[168:171], v[194:197], v[32:35]
	v_mfma_f32_16x16x32_bf16 v[20:23], v[160:163], v[202:205], v[20:23]
	v_mfma_f32_16x16x32_bf16 v[16:19], v[168:171], v[202:205], v[16:19]
	v_mfma_f32_16x16x32_bf16 v[4:7], v[160:163], v[210:213], v[4:7]
	v_mfma_f32_16x16x32_bf16 v[0:3], v[168:171], v[210:213], v[0:3]
	v_mfma_f32_16x16x32_bf16 v[52:55], v[164:167], v[190:193], v[52:55]
	v_mfma_f32_16x16x32_bf16 v[48:51], v[182:185], v[190:193], v[48:51]
	v_mfma_f32_16x16x32_bf16 v[36:39], v[164:167], v[198:201], v[36:39]
	v_mfma_f32_16x16x32_bf16 v[32:35], v[182:185], v[198:201], v[32:35]
	v_mfma_f32_16x16x32_bf16 v[20:23], v[164:167], v[206:209], v[20:23]
	v_mfma_f32_16x16x32_bf16 v[16:19], v[182:185], v[206:209], v[16:19]
	v_mfma_f32_16x16x32_bf16 v[4:7], v[164:167], v[216:219], v[4:7]
	v_mfma_f32_16x16x32_bf16 v[0:3], v[182:185], v[216:219], v[0:3]
	s_setprio 0
	s_barrier
	s_add_i32 s72, s72, 2
	s_add_u32 s30, s30, 0x100
	s_addc_u32 s31, s31, 0
	s_add_u32 s70, s70, 0x100
	s_addc_u32 s71, s71, 0
	s_cmp_gt_u32 s72, 13

.LBB0_1208:
	s_ashr_i32 s51, s50, 31
	s_lshl_b64 s[52:53], s[50:51], 19
	s_add_u32 s52, s46, s52
	s_addc_u32 s53, s47, s53
	s_and_b64 s[54:55], s[6:7], exec
	s_cselect_b32 s51, s53, s61
	s_cselect_b32 s57, s52, s60
	s_ashr_i32 s45, s44, 31
	s_lshl_b64 s[54:55], s[44:45], 19
	s_add_u32 s54, s66, s54
	s_addc_u32 s55, s67, s55
	s_and_b64 s[64:65], s[6:7], exec
	s_cselect_b32 s45, s55, s63
	s_cselect_b32 s59, s54, s62
	s_add_u32 s60, s60, 0x40080
	s_addc_u32 s61, s61, 0
	s_add_u32 s87, s62, 0x100
	s_addc_u32 s88, s63, 0
	s_mov_b32 s89, -2
	ds_read_b128 v[146:149], v216
	ds_read_b128 v[150:153], v216 offset:1024
	ds_read_b128 v[154:157], v216 offset:2048
	ds_read_b128 v[158:161], v216 offset:3072
	ds_read_b128 v[162:165], v217
	ds_read_b128 v[166:169], v217 offset:1024
	ds_read_b128 v[170:173], v217 offset:2048
	ds_read_b128 v[174:177], v217 offset:3072
	s_add_u32 s62, s60, 0xfffc0080
	s_addc_u32 s63, s61, -1
	s_cmp_eq_u32 s89, 12
	s_cselect_b32 s65, s51, s63
	s_cselect_b32 s64, s57, s62
	s_cselect_b32 s63, s45, s88
	s_cselect_b32 s62, s59, s87
	v_lshl_add_u64 v[220:221], s[60:61], 0, v[138:139]
	s_add_i32 m0, s69, 0xc000
	ds_read_b128 v[178:181], v218
	ds_read_b128 v[182:185], v218 offset:1024
	ds_read_b128 v[186:189], v218 offset:2048
	ds_read_b128 v[190:193], v218 offset:3072
	ds_read_b128 v[194:197], v218 offset:4096
	ds_read_b128 v[198:201], v218 offset:5120
	ds_read_b128 v[202:205], v218 offset:6144
	ds_read_b128 v[206:209], v218 offset:7168
	global_load_lds_dwordx4 v[220:221], off
	v_lshl_add_u64 v[220:221], s[60:61], 0, v[140:141]
	s_add_i32 m0, s69, 0xe000
	s_nop 0
	global_load_lds_dwordx4 v[220:221], off
	s_waitcnt vmcnt(8)
	s_waitcnt lgkmcnt(0)
	s_barrier
	s_setprio 1
	s_waitcnt lgkmcnt(0)
	v_mfma_f32_16x16x32_bf16 v[124:127], v[146:149], v[178:181], 0
	v_mfma_f32_16x16x32_bf16 v[60:63], v[154:157], v[178:181], 0
	v_mfma_f32_16x16x32_bf16 v[116:119], v[146:149], v[186:189], 0
	v_mfma_f32_16x16x32_bf16 v[52:55], v[154:157], v[186:189], 0
	v_mfma_f32_16x16x32_bf16 v[112:115], v[146:149], v[194:197], 0
	v_mfma_f32_16x16x32_bf16 v[48:51], v[154:157], v[194:197], 0
	v_mfma_f32_16x16x32_bf16 v[108:111], v[146:149], v[202:205], 0
	v_mfma_f32_16x16x32_bf16 v[40:43], v[154:157], v[202:205], 0
	v_mfma_f32_16x16x32_bf16 v[124:127], v[150:153], v[182:185], v[124:127]
	v_mfma_f32_16x16x32_bf16 v[60:63], v[158:161], v[182:185], v[60:63]
	v_mfma_f32_16x16x32_bf16 v[116:119], v[150:153], v[190:193], v[116:119]
	v_mfma_f32_16x16x32_bf16 v[52:55], v[158:161], v[190:193], v[52:55]
	v_mfma_f32_16x16x32_bf16 v[112:115], v[150:153], v[198:201], v[112:115]
	v_mfma_f32_16x16x32_bf16 v[48:51], v[158:161], v[198:201], v[48:51]
	v_mfma_f32_16x16x32_bf16 v[108:111], v[150:153], v[206:209], v[108:111]
	v_mfma_f32_16x16x32_bf16 v[40:43], v[158:161], v[206:209], v[40:43]
	s_setprio 0
	s_setprio 1
	v_mfma_f32_16x16x32_bf16 v[120:123], v[162:165], v[178:181], 0
	v_mfma_f32_16x16x32_bf16 v[56:59], v[170:173], v[178:181], 0
	v_mfma_f32_16x16x32_bf16 v[104:107], v[162:165], v[186:189], 0
	v_mfma_f32_16x16x32_bf16 v[44:47], v[170:173], v[186:189], 0
	v_mfma_f32_16x16x32_bf16 v[100:103], v[162:165], v[194:197], 0
	v_mfma_f32_16x16x32_bf16 v[36:39], v[170:173], v[194:197], 0
	v_mfma_f32_16x16x32_bf16 v[96:99], v[162:165], v[202:205], 0
	v_mfma_f32_16x16x32_bf16 v[32:35], v[170:173], v[202:205], 0
	v_mfma_f32_16x16x32_bf16 v[120:123], v[166:169], v[182:185], v[120:123]
	v_mfma_f32_16x16x32_bf16 v[56:59], v[174:177], v[182:185], v[56:59]
	v_mfma_f32_16x16x32_bf16 v[104:107], v[166:169], v[190:193], v[104:107]
	v_mfma_f32_16x16x32_bf16 v[44:47], v[174:177], v[190:193], v[44:47]
	v_mfma_f32_16x16x32_bf16 v[100:103], v[166:169], v[198:201], v[100:103]
	v_mfma_f32_16x16x32_bf16 v[36:39], v[174:177], v[198:201], v[36:39]
	v_mfma_f32_16x16x32_bf16 v[96:99], v[166:169], v[206:209], v[96:99]
	v_mfma_f32_16x16x32_bf16 v[32:35], v[174:177], v[206:209], v[32:35]
	s_setprio 0
	s_barrier
	s_add_i32 s90, s82, s68
	v_lshl_add_u64 v[220:221], s[62:63], 0, v[128:129]
	s_mov_b32 m0, s90
	ds_read_b128 v[178:181], v218 offset:16384
	ds_read_b128 v[182:185], v218 offset:17408
	ds_read_b128 v[186:189], v218 offset:18432
	ds_read_b128 v[190:193], v218 offset:19456
	ds_read_b128 v[194:197], v218 offset:20480
	ds_read_b128 v[198:201], v218 offset:21504
	ds_read_b128 v[202:205], v218 offset:22528
	ds_read_b128 v[206:209], v218 offset:23552
	global_load_lds_dwordx4 v[220:221], off
	s_add_i32 m0, s90, 0x2000
	s_add_u32 s90, s62, 0x40000
	v_lshl_add_u64 v[222:223], s[62:63], 0, v[130:131]
	s_addc_u32 s91, s63, 0
	s_add_i32 s92, s83, s68
	global_load_lds_dwordx4 v[222:223], off
	v_lshl_add_u64 v[224:225], s[90:91], 0, v[128:129]
	s_mov_b32 m0, s92
	v_lshl_add_u64 v[226:227], s[64:65], 0, v[130:131]
	global_load_lds_dwordx4 v[224:225], off
	v_lshl_add_u64 v[224:225], s[90:91], 0, v[130:131]
	s_add_i32 m0, s92, 0x2000
	s_nop 0
	global_load_lds_dwordx4 v[224:225], off
	v_lshl_add_u64 v[224:225], s[64:65], 0, v[128:129]
	s_mov_b32 m0, s69
	s_nop 0
	global_load_lds_dwordx4 v[224:225], off
	s_mov_b32 m0, s70
	s_nop 0
	global_load_lds_dwordx4 v[226:227], off
	s_waitcnt vmcnt(8)
	s_waitcnt lgkmcnt(0)
	s_barrier
	s_setprio 1
	s_waitcnt lgkmcnt(0)
	v_mfma_f32_16x16x32_bf16 v[92:95], v[146:149], v[178:181], 0
	v_mfma_f32_16x16x32_bf16 v[28:31], v[154:157], v[178:181], 0
	v_mfma_f32_16x16x32_bf16 v[84:87], v[146:149], v[186:189], 0
	v_mfma_f32_16x16x32_bf16 v[20:23], v[154:157], v[186:189], 0
	v_mfma_f32_16x16x32_bf16 v[80:83], v[146:149], v[194:197], 0
	v_mfma_f32_16x16x32_bf16 v[16:19], v[154:157], v[194:197], 0
	v_mfma_f32_16x16x32_bf16 v[76:79], v[146:149], v[202:205], 0
	v_mfma_f32_16x16x32_bf16 v[8:11], v[154:157], v[202:205], 0
	v_mfma_f32_16x16x32_bf16 v[92:95], v[150:153], v[182:185], v[92:95]
	v_mfma_f32_16x16x32_bf16 v[28:31], v[158:161], v[182:185], v[28:31]
	v_mfma_f32_16x16x32_bf16 v[84:87], v[150:153], v[190:193], v[84:87]
	v_mfma_f32_16x16x32_bf16 v[20:23], v[158:161], v[190:193], v[20:23]
	v_mfma_f32_16x16x32_bf16 v[80:83], v[150:153], v[198:201], v[80:83]
	v_mfma_f32_16x16x32_bf16 v[16:19], v[158:161], v[198:201], v[16:19]
	v_mfma_f32_16x16x32_bf16 v[76:79], v[150:153], v[206:209], v[76:79]
	v_mfma_f32_16x16x32_bf16 v[8:11], v[158:161], v[206:209], v[8:11]
	s_setprio 0
	s_setprio 1
	v_mfma_f32_16x16x32_bf16 v[88:91], v[162:165], v[178:181], 0
	v_mfma_f32_16x16x32_bf16 v[24:27], v[170:173], v[178:181], 0
	v_mfma_f32_16x16x32_bf16 v[72:75], v[162:165], v[186:189], 0
	v_mfma_f32_16x16x32_bf16 v[12:15], v[170:173], v[186:189], 0
	v_mfma_f32_16x16x32_bf16 v[68:71], v[162:165], v[194:197], 0
	v_mfma_f32_16x16x32_bf16 v[4:7], v[170:173], v[194:197], 0
	v_mfma_f32_16x16x32_bf16 v[64:67], v[162:165], v[202:205], 0
	v_mfma_f32_16x16x32_bf16 v[0:3], v[170:173], v[202:205], 0
	v_mfma_f32_16x16x32_bf16 v[88:91], v[166:169], v[182:185], v[88:91]
	v_mfma_f32_16x16x32_bf16 v[24:27], v[174:177], v[182:185], v[24:27]
	v_mfma_f32_16x16x32_bf16 v[72:75], v[166:169], v[190:193], v[72:75]
	v_mfma_f32_16x16x32_bf16 v[12:15], v[174:177], v[190:193], v[12:15]
	v_mfma_f32_16x16x32_bf16 v[68:71], v[166:169], v[198:201], v[68:71]
	v_mfma_f32_16x16x32_bf16 v[4:7], v[174:177], v[198:201], v[4:7]
	v_mfma_f32_16x16x32_bf16 v[64:67], v[166:169], v[206:209], v[64:67]
	v_mfma_f32_16x16x32_bf16 v[0:3], v[174:177], v[206:209], v[0:3]
	s_setprio 0
	s_barrier
	s_add_i32 s90, 0, 0x18000
	s_add_i32 s91, 0, 0x1c000
	v_add_u32_e32 v158, s90, v211
	v_add_u32_e32 v174, s91, v211
	ds_read_b128 v[146:149], v158
	ds_read_b128 v[150:153], v158 offset:1024
	ds_read_b128 v[154:157], v158 offset:2048
	ds_read_b128 v[158:161], v158 offset:3072
	ds_read_b128 v[162:165], v174
	ds_read_b128 v[166:169], v174 offset:1024
	ds_read_b128 v[170:173], v174 offset:2048
	ds_read_b128 v[174:177], v174 offset:3072
	s_add_u32 s64, s64, 0x40000
	s_addc_u32 s65, s65, 0
	s_mov_b32 m0, s71
	v_lshl_add_u64 v[228:229], s[64:65], 0, v[128:129]
	ds_read_b128 v[178:181], v218 offset:32768
	ds_read_b128 v[182:185], v218 offset:33792
	ds_read_b128 v[186:189], v218 offset:34816
	ds_read_b128 v[190:193], v218 offset:35840
	ds_read_b128 v[194:197], v218 offset:36864
	ds_read_b128 v[198:201], v218 offset:37888
	ds_read_b128 v[202:205], v218 offset:38912
	ds_read_b128 v[206:209], v218 offset:39936
	global_load_lds_dwordx4 v[228:229], off
	v_lshl_add_u64 v[228:229], s[64:65], 0, v[130:131]
	s_mov_b32 m0, s72
	s_nop 0
	global_load_lds_dwordx4 v[228:229], off
	s_waitcnt vmcnt(8)
	s_waitcnt lgkmcnt(0)
	s_barrier
	s_setprio 1
	s_waitcnt lgkmcnt(0)
	v_mfma_f32_16x16x32_bf16 v[124:127], v[146:149], v[178:181], v[124:127]
	v_mfma_f32_16x16x32_bf16 v[60:63], v[154:157], v[178:181], v[60:63]
	v_mfma_f32_16x16x32_bf16 v[116:119], v[146:149], v[186:189], v[116:119]
	v_mfma_f32_16x16x32_bf16 v[52:55], v[154:157], v[186:189], v[52:55]
	v_mfma_f32_16x16x32_bf16 v[112:115], v[146:149], v[194:197], v[112:115]
	v_mfma_f32_16x16x32_bf16 v[48:51], v[154:157], v[194:197], v[48:51]
	v_mfma_f32_16x16x32_bf16 v[108:111], v[146:149], v[202:205], v[108:111]
	v_mfma_f32_16x16x32_bf16 v[40:43], v[154:157], v[202:205], v[40:43]
	v_mfma_f32_16x16x32_bf16 v[124:127], v[150:153], v[182:185], v[124:127]
	v_mfma_f32_16x16x32_bf16 v[60:63], v[158:161], v[182:185], v[60:63]
	v_mfma_f32_16x16x32_bf16 v[116:119], v[150:153], v[190:193], v[116:119]
	v_mfma_f32_16x16x32_bf16 v[52:55], v[158:161], v[190:193], v[52:55]
	v_mfma_f32_16x16x32_bf16 v[112:115], v[150:153], v[198:201], v[112:115]
	v_mfma_f32_16x16x32_bf16 v[48:51], v[158:161], v[198:201], v[48:51]
	v_mfma_f32_16x16x32_bf16 v[108:111], v[150:153], v[206:209], v[108:111]
	v_mfma_f32_16x16x32_bf16 v[40:43], v[158:161], v[206:209], v[40:43]
	s_setprio 0
	s_setprio 1
	v_mfma_f32_16x16x32_bf16 v[120:123], v[162:165], v[178:181], v[120:123]
	v_mfma_f32_16x16x32_bf16 v[56:59], v[170:173], v[178:181], v[56:59]
	v_mfma_f32_16x16x32_bf16 v[104:107], v[162:165], v[186:189], v[104:107]
	v_mfma_f32_16x16x32_bf16 v[44:47], v[170:173], v[186:189], v[44:47]
	v_mfma_f32_16x16x32_bf16 v[100:103], v[162:165], v[194:197], v[100:103]
	v_mfma_f32_16x16x32_bf16 v[36:39], v[170:173], v[194:197], v[36:39]
	v_mfma_f32_16x16x32_bf16 v[96:99], v[162:165], v[202:205], v[96:99]
	v_mfma_f32_16x16x32_bf16 v[32:35], v[170:173], v[202:205], v[32:35]
	v_mfma_f32_16x16x32_bf16 v[120:123], v[166:169], v[182:185], v[120:123]
	v_mfma_f32_16x16x32_bf16 v[56:59], v[174:177], v[182:185], v[56:59]
	v_mfma_f32_16x16x32_bf16 v[104:107], v[166:169], v[190:193], v[104:107]
	v_mfma_f32_16x16x32_bf16 v[44:47], v[174:177], v[190:193], v[44:47]
	v_mfma_f32_16x16x32_bf16 v[100:103], v[166:169], v[198:201], v[100:103]
	v_mfma_f32_16x16x32_bf16 v[36:39], v[174:177], v[198:201], v[36:39]
	v_mfma_f32_16x16x32_bf16 v[96:99], v[166:169], v[206:209], v[96:99]
	v_mfma_f32_16x16x32_bf16 v[32:35], v[174:177], v[206:209], v[32:35]
	s_setprio 0
	s_barrier
	s_add_i32 s64, s90, s68
	v_lshl_add_u64 v[220:221], v[220:221], 0, s[20:21]
	s_mov_b32 m0, s64
	ds_read_b128 v[178:181], v218 offset:49152
	ds_read_b128 v[182:185], v218 offset:50176
	ds_read_b128 v[186:189], v218 offset:51200
	ds_read_b128 v[190:193], v218 offset:52224
	ds_read_b128 v[194:197], v218 offset:53248
	ds_read_b128 v[198:201], v218 offset:54272
	ds_read_b128 v[202:205], v218 offset:55296
	ds_read_b128 v[206:209], v218 offset:56320
	global_load_lds_dwordx4 v[220:221], off
	s_add_i32 m0, s64, 0x2000
	s_add_u32 s62, s62, 0x40080
	v_lshl_add_u64 v[220:221], v[222:223], 0, s[20:21]
	s_addc_u32 s63, s63, 0
	s_add_i32 s64, s91, s68
	global_load_lds_dwordx4 v[220:221], off
	v_lshl_add_u64 v[220:221], s[62:63], 0, v[128:129]
	s_mov_b32 m0, s64
	s_nop 0
	global_load_lds_dwordx4 v[220:221], off
	v_lshl_add_u64 v[220:221], s[62:63], 0, v[130:131]
	s_add_i32 m0, s64, 0x2000
	s_nop 0
	global_load_lds_dwordx4 v[220:221], off
	v_lshl_add_u64 v[220:221], v[224:225], 0, s[20:21]
	s_mov_b32 m0, s79
	s_nop 0
	global_load_lds_dwordx4 v[220:221], off
	v_lshl_add_u64 v[220:221], v[226:227], 0, s[20:21]
	s_mov_b32 m0, s80
	s_nop 0
	global_load_lds_dwordx4 v[220:221], off
	s_waitcnt vmcnt(8)
	s_waitcnt lgkmcnt(0)
	s_barrier
	s_setprio 1
	s_waitcnt lgkmcnt(0)
	v_mfma_f32_16x16x32_bf16 v[92:95], v[146:149], v[178:181], v[92:95]
	v_mfma_f32_16x16x32_bf16 v[28:31], v[154:157], v[178:181], v[28:31]
	v_mfma_f32_16x16x32_bf16 v[84:87], v[146:149], v[186:189], v[84:87]
	v_mfma_f32_16x16x32_bf16 v[20:23], v[154:157], v[186:189], v[20:23]
	v_mfma_f32_16x16x32_bf16 v[80:83], v[146:149], v[194:197], v[80:83]
	v_mfma_f32_16x16x32_bf16 v[16:19], v[154:157], v[194:197], v[16:19]
	v_mfma_f32_16x16x32_bf16 v[76:79], v[146:149], v[202:205], v[76:79]
	v_mfma_f32_16x16x32_bf16 v[8:11], v[154:157], v[202:205], v[8:11]
	v_mfma_f32_16x16x32_bf16 v[92:95], v[150:153], v[182:185], v[92:95]
	v_mfma_f32_16x16x32_bf16 v[28:31], v[158:161], v[182:185], v[28:31]
	v_mfma_f32_16x16x32_bf16 v[84:87], v[150:153], v[190:193], v[84:87]
	v_mfma_f32_16x16x32_bf16 v[20:23], v[158:161], v[190:193], v[20:23]
	v_mfma_f32_16x16x32_bf16 v[80:83], v[150:153], v[198:201], v[80:83]
	v_mfma_f32_16x16x32_bf16 v[16:19], v[158:161], v[198:201], v[16:19]
	v_mfma_f32_16x16x32_bf16 v[76:79], v[150:153], v[206:209], v[76:79]
	v_mfma_f32_16x16x32_bf16 v[8:11], v[158:161], v[206:209], v[8:11]
	s_setprio 0
	s_setprio 1
	v_mfma_f32_16x16x32_bf16 v[88:91], v[162:165], v[178:181], v[88:91]
	v_mfma_f32_16x16x32_bf16 v[24:27], v[170:173], v[178:181], v[24:27]
	v_mfma_f32_16x16x32_bf16 v[72:75], v[162:165], v[186:189], v[72:75]
	v_mfma_f32_16x16x32_bf16 v[12:15], v[170:173], v[186:189], v[12:15]
	v_mfma_f32_16x16x32_bf16 v[68:71], v[162:165], v[194:197], v[68:71]
	v_mfma_f32_16x16x32_bf16 v[4:7], v[170:173], v[194:197], v[4:7]
	v_mfma_f32_16x16x32_bf16 v[64:67], v[162:165], v[202:205], v[64:67]
	v_mfma_f32_16x16x32_bf16 v[0:3], v[170:173], v[202:205], v[0:3]
	v_mfma_f32_16x16x32_bf16 v[88:91], v[166:169], v[182:185], v[88:91]
	v_mfma_f32_16x16x32_bf16 v[24:27], v[174:177], v[182:185], v[24:27]
	v_mfma_f32_16x16x32_bf16 v[72:75], v[166:169], v[190:193], v[72:75]
	v_mfma_f32_16x16x32_bf16 v[12:15], v[174:177], v[190:193], v[12:15]
	v_mfma_f32_16x16x32_bf16 v[68:71], v[166:169], v[198:201], v[68:71]
	v_mfma_f32_16x16x32_bf16 v[4:7], v[174:177], v[198:201], v[4:7]
	v_mfma_f32_16x16x32_bf16 v[64:67], v[166:169], v[206:209], v[64:67]
	v_mfma_f32_16x16x32_bf16 v[0:3], v[174:177], v[206:209], v[0:3]
	s_setprio 0
	s_barrier
	s_add_i32 s89, s89, 2
	s_add_u32 s60, s60, 0x100
	s_addc_u32 s61, s61, 0
	s_add_u32 s87, s87, 0x100
	s_addc_u32 s88, s88, 0
	s_cmp_gt_u32 s89, 13

.LBB0_1360:
	s_add_u32 s45, s16, 0x100
	s_addc_u32 s50, s17, 0
	s_mov_b32 s51, -2
	ds_read_b128 v[142:145], v157
	ds_read_b128 v[146:149], v157 offset:1024
	ds_read_b128 v[150:153], v157 offset:2048
	ds_read_b128 v[160:163], v157 offset:3072
	ds_read_b128 v[164:167], v158
	ds_read_b128 v[168:171], v158 offset:1024
	ds_read_b128 v[172:175], v158 offset:2048
	ds_read_b128 v[176:179], v158 offset:3072
	s_add_u32 s16, s14, 0x100
	s_addc_u32 s17, s15, 0
	s_cmp_eq_u32 s51, 40
	s_cselect_b32 s21, s3, s17
	s_cselect_b32 s20, s2, s16
	s_cselect_b32 s19, s13, s50
	s_cselect_b32 s18, s12, s45
	v_lshl_add_u64 v[212:213], s[14:15], 0, v[136:137]
	s_add_i32 m0, s29, 0xc000
	ds_read_b128 v[180:183], v159
	ds_read_b128 v[184:187], v159 offset:1024
	ds_read_b128 v[188:191], v159 offset:2048
	ds_read_b128 v[192:195], v159 offset:3072
	ds_read_b128 v[196:199], v159 offset:4096
	ds_read_b128 v[200:203], v159 offset:5120
	ds_read_b128 v[204:207], v159 offset:6144
	ds_read_b128 v[208:211], v159 offset:7168
	global_load_lds_dwordx4 v[212:213], off
	v_lshl_add_u64 v[212:213], s[14:15], 0, v[138:139]
	s_add_i32 m0, s29, 0xe000
	s_nop 0
	global_load_lds_dwordx4 v[212:213], off
	s_waitcnt vmcnt(8)
	s_waitcnt lgkmcnt(0)
	s_barrier
	s_setprio 1
	s_waitcnt lgkmcnt(0)
	v_mfma_f32_16x16x32_bf16 v[124:127], v[142:145], v[180:183], 0
	v_mfma_f32_16x16x32_bf16 v[120:123], v[150:153], v[180:183], 0
	v_mfma_f32_16x16x32_bf16 v[108:111], v[142:145], v[188:191], 0
	v_mfma_f32_16x16x32_bf16 v[104:107], v[150:153], v[188:191], 0
	v_mfma_f32_16x16x32_bf16 v[92:95], v[142:145], v[196:199], 0
	v_mfma_f32_16x16x32_bf16 v[88:91], v[150:153], v[196:199], 0
	v_mfma_f32_16x16x32_bf16 v[80:83], v[142:145], v[204:207], 0
	v_mfma_f32_16x16x32_bf16 v[72:75], v[150:153], v[204:207], 0
	v_mfma_f32_16x16x32_bf16 v[124:127], v[146:149], v[184:187], v[124:127]
	v_mfma_f32_16x16x32_bf16 v[120:123], v[160:163], v[184:187], v[120:123]
	v_mfma_f32_16x16x32_bf16 v[108:111], v[146:149], v[192:195], v[108:111]
	v_mfma_f32_16x16x32_bf16 v[104:107], v[160:163], v[192:195], v[104:107]
	v_mfma_f32_16x16x32_bf16 v[92:95], v[146:149], v[200:203], v[92:95]
	v_mfma_f32_16x16x32_bf16 v[88:91], v[160:163], v[200:203], v[88:91]
	v_mfma_f32_16x16x32_bf16 v[80:83], v[146:149], v[208:211], v[80:83]
	v_mfma_f32_16x16x32_bf16 v[72:75], v[160:163], v[208:211], v[72:75]
	s_setprio 0
	s_setprio 1
	v_mfma_f32_16x16x32_bf16 v[116:119], v[164:167], v[180:183], 0
	v_mfma_f32_16x16x32_bf16 v[112:115], v[172:175], v[180:183], 0
	v_mfma_f32_16x16x32_bf16 v[100:103], v[164:167], v[188:191], 0
	v_mfma_f32_16x16x32_bf16 v[96:99], v[172:175], v[188:191], 0
	v_mfma_f32_16x16x32_bf16 v[84:87], v[164:167], v[196:199], 0
	v_mfma_f32_16x16x32_bf16 v[76:79], v[172:175], v[196:199], 0
	v_mfma_f32_16x16x32_bf16 v[68:71], v[164:167], v[204:207], 0
	v_mfma_f32_16x16x32_bf16 v[64:67], v[172:175], v[204:207], 0
	v_mfma_f32_16x16x32_bf16 v[116:119], v[168:171], v[184:187], v[116:119]
	v_mfma_f32_16x16x32_bf16 v[112:115], v[176:179], v[184:187], v[112:115]
	v_mfma_f32_16x16x32_bf16 v[100:103], v[168:171], v[192:195], v[100:103]
	v_mfma_f32_16x16x32_bf16 v[96:99], v[176:179], v[192:195], v[96:99]
	v_mfma_f32_16x16x32_bf16 v[84:87], v[168:171], v[200:203], v[84:87]
	v_mfma_f32_16x16x32_bf16 v[76:79], v[176:179], v[200:203], v[76:79]
	v_mfma_f32_16x16x32_bf16 v[68:71], v[168:171], v[208:211], v[68:71]
	v_mfma_f32_16x16x32_bf16 v[64:67], v[176:179], v[208:211], v[64:67]
	s_setprio 0
	s_barrier
	s_add_i32 s14, s4, s27
	v_lshl_add_u64 v[212:213], s[18:19], 0, v[132:133]
	s_mov_b32 m0, s14
	ds_read_b128 v[180:183], v159 offset:16384
	ds_read_b128 v[184:187], v159 offset:17408
	ds_read_b128 v[188:191], v159 offset:18432
	ds_read_b128 v[192:195], v159 offset:19456
	ds_read_b128 v[196:199], v159 offset:20480
	ds_read_b128 v[200:203], v159 offset:21504
	ds_read_b128 v[204:207], v159 offset:22528
	ds_read_b128 v[208:211], v159 offset:23552
	global_load_lds_dwordx4 v[212:213], off
	s_add_i32 m0, s14, 0x2000
	s_add_u32 s14, s18, 0xb0000
	v_lshl_add_u64 v[214:215], s[18:19], 0, v[128:129]
	s_addc_u32 s15, s19, 0
	s_add_i32 s52, s40, s27
	global_load_lds_dwordx4 v[214:215], off
	v_lshl_add_u64 v[216:217], s[14:15], 0, v[132:133]
	s_mov_b32 m0, s52
	v_lshl_add_u64 v[218:219], s[20:21], 0, v[130:131]
	global_load_lds_dwordx4 v[216:217], off
	v_lshl_add_u64 v[216:217], s[14:15], 0, v[128:129]
	s_add_i32 m0, s52, 0x2000
	s_nop 0
	global_load_lds_dwordx4 v[216:217], off
	v_lshl_add_u64 v[216:217], s[20:21], 0, v[134:135]
	s_mov_b32 m0, s29
	s_nop 0
	global_load_lds_dwordx4 v[216:217], off
	s_mov_b32 m0, s30
	s_nop 0
	global_load_lds_dwordx4 v[218:219], off
	s_waitcnt vmcnt(8)
	s_waitcnt lgkmcnt(0)
	s_barrier
	s_setprio 1
	s_waitcnt lgkmcnt(0)
	v_mfma_f32_16x16x32_bf16 v[60:63], v[142:145], v[180:183], 0
	v_mfma_f32_16x16x32_bf16 v[56:59], v[150:153], v[180:183], 0
	v_mfma_f32_16x16x32_bf16 v[44:47], v[142:145], v[188:191], 0
	v_mfma_f32_16x16x32_bf16 v[40:43], v[150:153], v[188:191], 0
	v_mfma_f32_16x16x32_bf16 v[36:39], v[142:145], v[196:199], 0
	v_mfma_f32_16x16x32_bf16 v[24:27], v[150:153], v[196:199], 0
	v_mfma_f32_16x16x32_bf16 v[16:19], v[142:145], v[204:207], 0
	v_mfma_f32_16x16x32_bf16 v[8:11], v[150:153], v[204:207], 0
	v_mfma_f32_16x16x32_bf16 v[60:63], v[146:149], v[184:187], v[60:63]
	v_mfma_f32_16x16x32_bf16 v[56:59], v[160:163], v[184:187], v[56:59]
	v_mfma_f32_16x16x32_bf16 v[44:47], v[146:149], v[192:195], v[44:47]
	v_mfma_f32_16x16x32_bf16 v[40:43], v[160:163], v[192:195], v[40:43]
	v_mfma_f32_16x16x32_bf16 v[36:39], v[146:149], v[200:203], v[36:39]
	v_mfma_f32_16x16x32_bf16 v[24:27], v[160:163], v[200:203], v[24:27]
	v_mfma_f32_16x16x32_bf16 v[16:19], v[146:149], v[208:211], v[16:19]
	v_mfma_f32_16x16x32_bf16 v[8:11], v[160:163], v[208:211], v[8:11]
	s_setprio 0
	s_setprio 1
	v_mfma_f32_16x16x32_bf16 v[52:55], v[164:167], v[180:183], 0
	v_mfma_f32_16x16x32_bf16 v[48:51], v[172:175], v[180:183], 0
	v_mfma_f32_16x16x32_bf16 v[32:35], v[164:167], v[188:191], 0
	v_mfma_f32_16x16x32_bf16 v[28:31], v[172:175], v[188:191], 0
	v_mfma_f32_16x16x32_bf16 v[20:23], v[164:167], v[196:199], 0
	v_mfma_f32_16x16x32_bf16 v[12:15], v[172:175], v[196:199], 0
	v_mfma_f32_16x16x32_bf16 v[4:7], v[164:167], v[204:207], 0
	v_mfma_f32_16x16x32_bf16 v[0:3], v[172:175], v[204:207], 0
	v_mfma_f32_16x16x32_bf16 v[52:55], v[168:171], v[184:187], v[52:55]
	v_mfma_f32_16x16x32_bf16 v[48:51], v[176:179], v[184:187], v[48:51]
	v_mfma_f32_16x16x32_bf16 v[32:35], v[168:171], v[192:195], v[32:35]
	v_mfma_f32_16x16x32_bf16 v[28:31], v[176:179], v[192:195], v[28:31]
	v_mfma_f32_16x16x32_bf16 v[20:23], v[168:171], v[200:203], v[20:23]
	v_mfma_f32_16x16x32_bf16 v[12:15], v[176:179], v[200:203], v[12:15]
	v_mfma_f32_16x16x32_bf16 v[4:7], v[168:171], v[208:211], v[4:7]
	v_mfma_f32_16x16x32_bf16 v[0:3], v[176:179], v[208:211], v[0:3]
	s_setprio 0
	s_barrier
	s_add_i32 s52, 0, 0x18000
	s_add_i32 s53, 0, 0x1c000
	v_add_u32_e32 v160, s52, v155
	v_add_u32_e32 v176, s53, v155
	ds_read_b128 v[142:145], v160
	ds_read_b128 v[146:149], v160 offset:1024
	ds_read_b128 v[150:153], v160 offset:2048
	ds_read_b128 v[160:163], v160 offset:3072
	ds_read_b128 v[164:167], v176
	ds_read_b128 v[168:171], v176 offset:1024
	ds_read_b128 v[172:175], v176 offset:2048
	ds_read_b128 v[176:179], v176 offset:3072
	s_add_u32 s14, s20, 0xb0000
	s_addc_u32 s15, s21, 0
	s_mov_b32 m0, s31
	v_lshl_add_u64 v[220:221], s[14:15], 0, v[134:135]
	ds_read_b128 v[180:183], v159 offset:32768
	ds_read_b128 v[184:187], v159 offset:33792
	ds_read_b128 v[188:191], v159 offset:34816
	ds_read_b128 v[192:195], v159 offset:35840
	ds_read_b128 v[196:199], v159 offset:36864
	ds_read_b128 v[200:203], v159 offset:37888
	ds_read_b128 v[204:207], v159 offset:38912
	ds_read_b128 v[208:211], v159 offset:39936
	global_load_lds_dwordx4 v[220:221], off
	v_lshl_add_u64 v[220:221], s[14:15], 0, v[130:131]
	s_mov_b32 m0, s34
	s_nop 0
	global_load_lds_dwordx4 v[220:221], off
	s_waitcnt vmcnt(8)
	s_waitcnt lgkmcnt(0)
	s_barrier
	s_setprio 1
	s_waitcnt lgkmcnt(0)
	v_mfma_f32_16x16x32_bf16 v[124:127], v[142:145], v[180:183], v[124:127]
	v_mfma_f32_16x16x32_bf16 v[120:123], v[150:153], v[180:183], v[120:123]
	v_mfma_f32_16x16x32_bf16 v[108:111], v[142:145], v[188:191], v[108:111]
	v_mfma_f32_16x16x32_bf16 v[104:107], v[150:153], v[188:191], v[104:107]
	v_mfma_f32_16x16x32_bf16 v[92:95], v[142:145], v[196:199], v[92:95]
	v_mfma_f32_16x16x32_bf16 v[88:91], v[150:153], v[196:199], v[88:91]
	v_mfma_f32_16x16x32_bf16 v[80:83], v[142:145], v[204:207], v[80:83]
	v_mfma_f32_16x16x32_bf16 v[72:75], v[150:153], v[204:207], v[72:75]
	v_mfma_f32_16x16x32_bf16 v[124:127], v[146:149], v[184:187], v[124:127]
	v_mfma_f32_16x16x32_bf16 v[120:123], v[160:163], v[184:187], v[120:123]
	v_mfma_f32_16x16x32_bf16 v[108:111], v[146:149], v[192:195], v[108:111]
	v_mfma_f32_16x16x32_bf16 v[104:107], v[160:163], v[192:195], v[104:107]
	v_mfma_f32_16x16x32_bf16 v[92:95], v[146:149], v[200:203], v[92:95]
	v_mfma_f32_16x16x32_bf16 v[88:91], v[160:163], v[200:203], v[88:91]
	v_mfma_f32_16x16x32_bf16 v[80:83], v[146:149], v[208:211], v[80:83]
	v_mfma_f32_16x16x32_bf16 v[72:75], v[160:163], v[208:211], v[72:75]
	s_setprio 0
	s_setprio 1
	v_mfma_f32_16x16x32_bf16 v[116:119], v[164:167], v[180:183], v[116:119]
	v_mfma_f32_16x16x32_bf16 v[112:115], v[172:175], v[180:183], v[112:115]
	v_mfma_f32_16x16x32_bf16 v[100:103], v[164:167], v[188:191], v[100:103]
	v_mfma_f32_16x16x32_bf16 v[96:99], v[172:175], v[188:191], v[96:99]
	v_mfma_f32_16x16x32_bf16 v[84:87], v[164:167], v[196:199], v[84:87]
	v_mfma_f32_16x16x32_bf16 v[76:79], v[172:175], v[196:199], v[76:79]
	v_mfma_f32_16x16x32_bf16 v[68:71], v[164:167], v[204:207], v[68:71]
	v_mfma_f32_16x16x32_bf16 v[64:67], v[172:175], v[204:207], v[64:67]
	v_mfma_f32_16x16x32_bf16 v[116:119], v[168:171], v[184:187], v[116:119]
	v_mfma_f32_16x16x32_bf16 v[112:115], v[176:179], v[184:187], v[112:115]
	v_mfma_f32_16x16x32_bf16 v[100:103], v[168:171], v[192:195], v[100:103]
	v_mfma_f32_16x16x32_bf16 v[96:99], v[176:179], v[192:195], v[96:99]
	v_mfma_f32_16x16x32_bf16 v[84:87], v[168:171], v[200:203], v[84:87]
	v_mfma_f32_16x16x32_bf16 v[76:79], v[176:179], v[200:203], v[76:79]
	v_mfma_f32_16x16x32_bf16 v[68:71], v[168:171], v[208:211], v[68:71]
	v_mfma_f32_16x16x32_bf16 v[64:67], v[176:179], v[208:211], v[64:67]
	s_setprio 0
	s_barrier
	s_add_i32 s14, s52, s27
	v_lshl_add_u64 v[212:213], v[212:213], 0, s[8:9]
	s_mov_b32 m0, s14
	ds_read_b128 v[180:183], v159 offset:49152
	ds_read_b128 v[184:187], v159 offset:50176
	ds_read_b128 v[188:191], v159 offset:51200
	ds_read_b128 v[192:195], v159 offset:52224
	ds_read_b128 v[196:199], v159 offset:53248
	ds_read_b128 v[200:203], v159 offset:54272
	ds_read_b128 v[204:207], v159 offset:55296
	ds_read_b128 v[208:211], v159 offset:56320
	global_load_lds_dwordx4 v[212:213], off
	s_add_i32 m0, s14, 0x2000
	s_add_u32 s14, s18, 0xb0080
	v_lshl_add_u64 v[212:213], v[214:215], 0, s[8:9]
	s_addc_u32 s15, s19, 0
	s_add_i32 s18, s53, s27
	global_load_lds_dwordx4 v[212:213], off
	v_lshl_add_u64 v[212:213], s[14:15], 0, v[132:133]
	s_mov_b32 m0, s18
	s_nop 0
	global_load_lds_dwordx4 v[212:213], off
	v_lshl_add_u64 v[212:213], s[14:15], 0, v[128:129]
	s_add_i32 m0, s18, 0x2000
	s_nop 0
	global_load_lds_dwordx4 v[212:213], off
	v_lshl_add_u64 v[212:213], v[216:217], 0, s[8:9]
	s_mov_b32 m0, s38
	s_nop 0
	global_load_lds_dwordx4 v[212:213], off
	v_lshl_add_u64 v[212:213], v[218:219], 0, s[8:9]
	s_mov_b32 m0, s39
	s_nop 0
	global_load_lds_dwordx4 v[212:213], off
	s_waitcnt vmcnt(8)
	s_waitcnt lgkmcnt(0)
	s_barrier
	s_setprio 1
	s_waitcnt lgkmcnt(0)
	v_mfma_f32_16x16x32_bf16 v[60:63], v[142:145], v[180:183], v[60:63]
	v_mfma_f32_16x16x32_bf16 v[56:59], v[150:153], v[180:183], v[56:59]
	v_mfma_f32_16x16x32_bf16 v[44:47], v[142:145], v[188:191], v[44:47]
	v_mfma_f32_16x16x32_bf16 v[40:43], v[150:153], v[188:191], v[40:43]
	v_mfma_f32_16x16x32_bf16 v[36:39], v[142:145], v[196:199], v[36:39]
	v_mfma_f32_16x16x32_bf16 v[24:27], v[150:153], v[196:199], v[24:27]
	v_mfma_f32_16x16x32_bf16 v[16:19], v[142:145], v[204:207], v[16:19]
	v_mfma_f32_16x16x32_bf16 v[8:11], v[150:153], v[204:207], v[8:11]
	v_mfma_f32_16x16x32_bf16 v[60:63], v[146:149], v[184:187], v[60:63]
	v_mfma_f32_16x16x32_bf16 v[56:59], v[160:163], v[184:187], v[56:59]
	v_mfma_f32_16x16x32_bf16 v[44:47], v[146:149], v[192:195], v[44:47]
	v_mfma_f32_16x16x32_bf16 v[40:43], v[160:163], v[192:195], v[40:43]
	v_mfma_f32_16x16x32_bf16 v[36:39], v[146:149], v[200:203], v[36:39]
	v_mfma_f32_16x16x32_bf16 v[24:27], v[160:163], v[200:203], v[24:27]
	v_mfma_f32_16x16x32_bf16 v[16:19], v[146:149], v[208:211], v[16:19]
	v_mfma_f32_16x16x32_bf16 v[8:11], v[160:163], v[208:211], v[8:11]
	s_setprio 0
	s_setprio 1
	v_mfma_f32_16x16x32_bf16 v[52:55], v[164:167], v[180:183], v[52:55]
	v_mfma_f32_16x16x32_bf16 v[48:51], v[172:175], v[180:183], v[48:51]
	v_mfma_f32_16x16x32_bf16 v[32:35], v[164:167], v[188:191], v[32:35]
	v_mfma_f32_16x16x32_bf16 v[28:31], v[172:175], v[188:191], v[28:31]
	v_mfma_f32_16x16x32_bf16 v[20:23], v[164:167], v[196:199], v[20:23]
	v_mfma_f32_16x16x32_bf16 v[12:15], v[172:175], v[196:199], v[12:15]
	v_mfma_f32_16x16x32_bf16 v[4:7], v[164:167], v[204:207], v[4:7]
	v_mfma_f32_16x16x32_bf16 v[0:3], v[172:175], v[204:207], v[0:3]
	v_mfma_f32_16x16x32_bf16 v[52:55], v[168:171], v[184:187], v[52:55]
	v_mfma_f32_16x16x32_bf16 v[48:51], v[176:179], v[184:187], v[48:51]
	v_mfma_f32_16x16x32_bf16 v[32:35], v[168:171], v[192:195], v[32:35]
	v_mfma_f32_16x16x32_bf16 v[28:31], v[176:179], v[192:195], v[28:31]
	v_mfma_f32_16x16x32_bf16 v[20:23], v[168:171], v[200:203], v[20:23]
	v_mfma_f32_16x16x32_bf16 v[12:15], v[176:179], v[200:203], v[12:15]
	v_mfma_f32_16x16x32_bf16 v[4:7], v[168:171], v[208:211], v[4:7]
	v_mfma_f32_16x16x32_bf16 v[0:3], v[176:179], v[208:211], v[0:3]
	s_setprio 0
	s_barrier
	s_add_i32 s51, s51, 2
	s_add_u32 s45, s45, 0x100
	s_addc_u32 s50, s50, 0
	s_cmp_gt_u32 s51, 41
	s_mov_b64 s[14:15], s[16:17]
